# all four GEMMs: a full unit enters the K loop through a peeled first iteration whose first MFMA per accumulator takes C=0 (no 127-register zeroing pass per unit); prologue transposes order reversed
# speedup vs baseline: 1.0059x; 1.0059x over previous
; #define PG8_STAGE(bufoff, gbase, voff) do { _Pragma("unroll") for (int _i = 0; _i < 2; ++_i) \
;         __builtin_amdgcn_global_load_lds((const unsigned*)((const char*)(gbase) + (voff)[_i]), (PG8_LAS unsigned*)(lds + (bufoff) + ldsw + _i * 8192), 16, 0, 0); } while (0)
; #define PG8_LDA(dst, b, h) do { _Pragma("unroll") for (int m = 0; m < 4; ++m) _Pragma("unroll") for (int k = 0; k < 2; ++k) dst[m][k] = *(const PG8_LAS bf16x8*)(lds + PG8_SA(b, h) + aoff + m * 2048 + k * 1024); } while (0)
; #define PG8_LDB(dst, b, h) do { _Pragma("unroll") for (int n = 0; n < 2; ++n) _Pragma("unroll") for (int k = 0; k < 2; ++k) dst[n][k] = *(const PG8_LAS bf16x8*)(lds + PG8_SB(b, h) + boff + n * 2048 + k * 1024); } while (0)
; #define PG8_MMA(ai, bj, At, Bt) do { __builtin_amdgcn_s_setprio(1); _Pragma("unroll") for (int m = 0; m < 4; ++m) _Pragma("unroll") for (int n = 0; n < 2; ++n) _Pragma("unroll") for (int k = 0; k < 2; ++k) \
;         acc[ai][bj][m][n] = __builtin_amdgcn_mfma_f32_16x16x32_bf16(Bt[n][k], At[m][k], acc[ai][bj][m][n], 0, 0, 0); __builtin_amdgcn_s_setprio(0); } while (0)
; #define PG8_WAIT_V(n) asm volatile("s_waitcnt vmcnt(" #n ")" ::: "memory")
; #define PG8_WAIT_L(n) asm volatile("s_waitcnt lgkmcnt(" #n ")" ::: "memory")
; #define PG8_BAR __builtin_amdgcn_s_barrier()
; template <class Epi, class Sched, bool ALIGN_EPI = false, bool SP2 = false>
; __device__ __forceinline__ void gemm_phase(PG8_LAS unsigned char* lds, const Gemm g, const Sched& S, const Epi& E) {
;     ...
;         const bool has_next = S.next(ui + 1, nxt);
;         const char* nA = has_next ? (const char*)g.A + (size_t)nxt.pm * tstep : cA; const char* nB = has_next ? (const char*)g.Bt + (size_t)nxt.pn * tstep : cB;
;         for (int t = 0; t < nt; t += 2) {
;             const bool last = (t == nt - 2);
;             const char* a1 = cA + (size_t)(t + 1) * kstep;
;             const char* a2 = last ? nA : cA + (size_t)(t + 2) * kstep; const char* b2 = last ? nB : cB + (size_t)(t + 2) * kstep;
;             const char* a3 = a2 + kstep; const char* b3 = b2 + kstep;
;             if (last && has_next) S.a_ready(nxt);
;             if constexpr (SP2) {
;             PG8_LDB(B0, 0, 0); PG8_LDB(B1, 0, 1); PG8_SCHED; PG8_LDA(At, 0, 0); PG8_STAGE(PG8_SA(1, 1), a1 + hstep, voffA);
;             PG8_WAIT_V(8); PG8_WAIT_L(0); PG8_BAR; PG8_MMA(0, 0, At, B0); PG8_MMA(0, 1, At, B1); PG8_BAR; PG8_SCHED;
.LBB0_162:
	s_ashr_i32 s21, s20, 31
	s_lshl_b64 s[22:23], s[20:21], 19
	s_add_u32 s22, s46, s22
	s_addc_u32 s23, s47, s23
	s_and_b64 s[24:25], s[6:7], exec
	s_cselect_b32 s21, s23, s31
	s_cselect_b32 s27, s22, s30
	s_ashr_i32 s19, s18, 31
	s_lshl_b64 s[24:25], s[18:19], 19
	s_add_u32 s24, s48, s24
	s_addc_u32 s25, s49, s25
	s_and_b64 s[40:41], s[6:7], exec
	s_cselect_b32 s19, s25, s35
	s_cselect_b32 s50, s24, s34
	s_add_u32 s30, s30, 0x40080
	s_addc_u32 s31, s31, 0
	s_add_u32 s52, s34, 0x100
	v_mov_b32_e32 v2, 0
	s_addc_u32 s54, s35, 0
	s_mov_b32 s62, -2
	s_and_b32 s98, s101, 7
	s_cmp_lg_u32 s98, 0
	s_cbranch_scc0 .Lpeel_u
	v_mov_b32_e32 v3, v2
	v_mov_b32_e32 v4, v2
	v_mov_b32_e32 v5, v2
	v_mov_b32_e32 v6, v2
	v_mov_b32_e32 v7, v2
	v_mov_b32_e32 v8, v2
	v_mov_b32_e32 v9, v2
	v_mov_b32_e32 v18, v2
	v_mov_b32_e32 v19, v2
	v_mov_b32_e32 v20, v2
	v_mov_b32_e32 v21, v2
	v_mov_b32_e32 v22, v2
	v_mov_b32_e32 v23, v2
	v_mov_b32_e32 v24, v2
	v_mov_b32_e32 v25, v2
	v_mov_b32_e32 v34, v2
	v_mov_b32_e32 v35, v2
	v_mov_b32_e32 v36, v2
	v_mov_b32_e32 v37, v2
	v_mov_b32_e32 v38, v2
	v_mov_b32_e32 v39, v2
	v_mov_b32_e32 v40, v2
	v_mov_b32_e32 v41, v2
	v_mov_b32_e32 v50, v2
	v_mov_b32_e32 v51, v2
	v_mov_b32_e32 v52, v2
	v_mov_b32_e32 v53, v2
	v_mov_b32_e32 v54, v2
	v_mov_b32_e32 v55, v2
	v_mov_b32_e32 v56, v2
	v_mov_b32_e32 v57, v2
	v_mov_b32_e32 v10, v2
	v_mov_b32_e32 v11, v2
	v_mov_b32_e32 v12, v2
	v_mov_b32_e32 v13, v2
	v_mov_b32_e32 v14, v2
	v_mov_b32_e32 v15, v2
	v_mov_b32_e32 v16, v2
	v_mov_b32_e32 v17, v2
	v_mov_b32_e32 v26, v2
	v_mov_b32_e32 v27, v2
	v_mov_b32_e32 v28, v2
	v_mov_b32_e32 v29, v2
	v_mov_b32_e32 v30, v2
	v_mov_b32_e32 v31, v2
	v_mov_b32_e32 v32, v2
	v_mov_b32_e32 v33, v2
	v_mov_b32_e32 v42, v2
	v_mov_b32_e32 v43, v2
	v_mov_b32_e32 v44, v2
	v_mov_b32_e32 v45, v2
	v_mov_b32_e32 v46, v2
	v_mov_b32_e32 v47, v2
	v_mov_b32_e32 v48, v2
	v_mov_b32_e32 v49, v2
	v_mov_b32_e32 v58, v2
	v_mov_b32_e32 v59, v2
	v_mov_b32_e32 v60, v2
	v_mov_b32_e32 v61, v2
	v_mov_b32_e32 v62, v2
	v_mov_b32_e32 v63, v2
	v_mov_b32_e32 v64, v2
	v_mov_b32_e32 v65, v2
	v_mov_b32_e32 v66, v2
	v_mov_b32_e32 v67, v2
	v_mov_b32_e32 v68, v2
	v_mov_b32_e32 v69, v2
	v_mov_b32_e32 v70, v2
	v_mov_b32_e32 v71, v2
	v_mov_b32_e32 v72, v2
	v_mov_b32_e32 v73, v2
	v_mov_b32_e32 v82, v2
	v_mov_b32_e32 v83, v2
	v_mov_b32_e32 v84, v2
	v_mov_b32_e32 v85, v2
	v_mov_b32_e32 v86, v2
	v_mov_b32_e32 v87, v2
	v_mov_b32_e32 v88, v2
	v_mov_b32_e32 v89, v2
	v_mov_b32_e32 v98, v2
	v_mov_b32_e32 v99, v2
	v_mov_b32_e32 v100, v2
	v_mov_b32_e32 v101, v2
	v_mov_b32_e32 v102, v2
	v_mov_b32_e32 v103, v2
	v_mov_b32_e32 v104, v2
	v_mov_b32_e32 v105, v2
	v_mov_b32_e32 v114, v2
	v_mov_b32_e32 v115, v2
	v_mov_b32_e32 v116, v2
	v_mov_b32_e32 v117, v2
	v_mov_b32_e32 v118, v2
	v_mov_b32_e32 v119, v2
	v_mov_b32_e32 v120, v2
	v_mov_b32_e32 v121, v2
	v_mov_b32_e32 v74, v2
	v_mov_b32_e32 v75, v2
	v_mov_b32_e32 v76, v2
	v_mov_b32_e32 v77, v2
	v_mov_b32_e32 v78, v2
	v_mov_b32_e32 v79, v2
	v_mov_b32_e32 v80, v2
	v_mov_b32_e32 v81, v2
	v_mov_b32_e32 v90, v2
	v_mov_b32_e32 v91, v2
	v_mov_b32_e32 v92, v2
	v_mov_b32_e32 v93, v2
	v_mov_b32_e32 v94, v2
	v_mov_b32_e32 v95, v2
	v_mov_b32_e32 v96, v2
	v_mov_b32_e32 v97, v2
	v_mov_b32_e32 v106, v2
	v_mov_b32_e32 v107, v2
	v_mov_b32_e32 v108, v2
	v_mov_b32_e32 v109, v2
	v_mov_b32_e32 v110, v2
	v_mov_b32_e32 v111, v2
	v_mov_b32_e32 v112, v2
	v_mov_b32_e32 v113, v2
	v_mov_b32_e32 v122, v2
	v_mov_b32_e32 v123, v2
	v_mov_b32_e32 v124, v2
	v_mov_b32_e32 v125, v2
	v_mov_b32_e32 v126, v2
	v_mov_b32_e32 v127, v2
	v_mov_b32_e32 v128, v2
	v_mov_b32_e32 v129, v2
	s_and_b32 s98, s101, 7
	s_cmp_eq_u32 s98, 1
	s_cbranch_scc1 .Lkuq_1
	s_and_b32 s98, s101, 7
	s_cmp_eq_u32 s98, 2
	s_cbranch_scc1 .Lkuq_2
	s_and_b32 s98, s101, 7
	s_cmp_eq_u32 s98, 3
	s_cbranch_scc1 .Lkuq_3
	s_and_b32 s98, s101, 7
	s_cmp_eq_u32 s98, 4
	s_cbranch_scc1 .Lkuq_4
	s_and_b32 s98, s101, 7
	s_cmp_eq_u32 s98, 5
	s_cbranch_scc1 .Lku_a0
	s_branch .Lku_a1
.Lpeel_u:
	s_add_u32 s34, s30, 0xfffc0080
	s_addc_u32 s35, s31, -1
	s_add_i32 s71, 0, 0x10000
	s_cmp_eq_u32 s62, 12
	s_cselect_b32 s41, s21, s35
	s_cselect_b32 s40, s27, s34
	v_add_u32_e32 v155, s71, v145
	s_cselect_b32 s35, s19, s54
	s_cselect_b32 s34, s50, s52
	s_add_i32 s74, 0, 0x14000
	ds_read_b128 v[156:159], v155
	ds_read_b128 v[160:163], v155 offset:1024
	ds_read_b128 v[164:167], v155 offset:2048
	ds_read_b128 v[168:171], v155 offset:3072
	v_add_u32_e32 v155, s74, v145
	ds_read_b128 v[172:175], v155
	ds_read_b128 v[176:179], v155 offset:1024
	ds_read_b128 v[180:183], v155 offset:2048
	ds_read_b128 v[208:211], v155 offset:3072
	v_lshl_add_u64 v[202:203], s[30:31], 0, v[134:135]
	s_add_i32 m0, s29, 0xc000
	ds_read_b128 v[212:215], v154
	ds_read_b128 v[216:219], v154 offset:1024
	ds_read_b128 v[220:223], v154 offset:2048
	ds_read_b128 v[224:227], v154 offset:3072
	ds_read_b128 v[228:231], v154 offset:4096
	ds_read_b128 v[232:235], v154 offset:5120
	ds_read_b128 v[236:239], v154 offset:6144
	ds_read_b128 v[240:243], v154 offset:7168
	global_load_lds_dwordx4 v[202:203], off
	v_lshl_add_u64 v[202:203], s[30:31], 0, v[136:137]
	s_add_i32 m0, s29, 0xe000
	s_nop 0
	global_load_lds_dwordx4 v[202:203], off
	s_waitcnt vmcnt(8)
	s_waitcnt lgkmcnt(0)
	s_barrier
; #define PG8_STAGE(bufoff, gbase, voff) do { _Pragma("unroll") for (int _i = 0; _i < 2; ++_i) \
;         __builtin_amdgcn_global_load_lds((const unsigned*)((const char*)(gbase) + (voff)[_i]), (PG8_LAS unsigned*)(lds + (bufoff) + ldsw + _i * 8192), 16, 0, 0); } while (0)
; #define PG8_LDA(dst, b, h) do { _Pragma("unroll") for (int m = 0; m < 4; ++m) _Pragma("unroll") for (int k = 0; k < 2; ++k) dst[m][k] = *(const PG8_LAS bf16x8*)(lds + PG8_SA(b, h) + aoff + m * 2048 + k * 1024); } while (0)
; #define PG8_LDB(dst, b, h) do { _Pragma("unroll") for (int n = 0; n < 2; ++n) _Pragma("unroll") for (int k = 0; k < 2; ++k) dst[n][k] = *(const PG8_LAS bf16x8*)(lds + PG8_SB(b, h) + boff + n * 2048 + k * 1024); } while (0)
; #define PG8_MMA(ai, bj, At, Bt) do { __builtin_amdgcn_s_setprio(1); _Pragma("unroll") for (int m = 0; m < 4; ++m) _Pragma("unroll") for (int n = 0; n < 2; ++n) _Pragma("unroll") for (int k = 0; k < 2; ++k) \
;         acc[ai][bj][m][n] = __builtin_amdgcn_mfma_f32_16x16x32_bf16(Bt[n][k], At[m][k], acc[ai][bj][m][n], 0, 0, 0); __builtin_amdgcn_s_setprio(0); } while (0)
; #define PG8_WAIT_V(n) asm volatile("s_waitcnt vmcnt(" #n ")" ::: "memory")
; #define PG8_WAIT_L(n) asm volatile("s_waitcnt lgkmcnt(" #n ")" ::: "memory")
; #define PG8_BAR __builtin_amdgcn_s_barrier()
; #define PG8_SCHED __builtin_amdgcn_sched_barrier(0)
; template <class Epi, class Sched, bool ALIGN_EPI = false, bool SP2 = false>
; __device__ __forceinline__ void gemm_phase(PG8_LAS unsigned char* lds, const Gemm g, const Sched& S, const Epi& E) {
;     ...
;             PG8_LDB(B0, 0, 0); PG8_LDB(B1, 0, 1); PG8_SCHED; PG8_LDA(At, 0, 0); PG8_STAGE(PG8_SA(1, 1), a1 + hstep, voffA);
;             PG8_WAIT_V(8); PG8_WAIT_L(0); PG8_BAR; PG8_MMA(0, 0, At, B0); PG8_MMA(0, 1, At, B1); PG8_BAR; PG8_SCHED;
;             PG8_LDA(At, 0, 1); PG8_STAGE(PG8_SB(0, 0), b2, voffB); PG8_STAGE(PG8_SB(0, 1), b2 + hstep, voffB); PG8_STAGE(PG8_SA(0, 0), a2, voffA);
;             PG8_WAIT_V(8); PG8_WAIT_L(0); PG8_BAR; PG8_MMA(1, 0, At, B0); PG8_MMA(1, 1, At, B1); PG8_BAR; PG8_SCHED;
	s_setprio 1
	s_waitcnt lgkmcnt(0)
	v_mfma_f32_16x16x32_bf16 v[126:129], v[156:159], v[212:215], 0
	v_mfma_f32_16x16x32_bf16 v[122:125], v[164:167], v[212:215], 0
	v_mfma_f32_16x16x32_bf16 v[110:113], v[156:159], v[220:223], 0
	v_mfma_f32_16x16x32_bf16 v[106:109], v[164:167], v[220:223], 0
	v_mfma_f32_16x16x32_bf16 v[94:97], v[156:159], v[228:231], 0
	v_mfma_f32_16x16x32_bf16 v[90:93], v[164:167], v[228:231], 0
	v_mfma_f32_16x16x32_bf16 v[78:81], v[156:159], v[236:239], 0
	v_mfma_f32_16x16x32_bf16 v[74:77], v[164:167], v[236:239], 0
	v_mfma_f32_16x16x32_bf16 v[126:129], v[160:163], v[216:219], v[126:129]
	v_mfma_f32_16x16x32_bf16 v[122:125], v[168:171], v[216:219], v[122:125]
	v_mfma_f32_16x16x32_bf16 v[110:113], v[160:163], v[224:227], v[110:113]
	v_mfma_f32_16x16x32_bf16 v[106:109], v[168:171], v[224:227], v[106:109]
	v_mfma_f32_16x16x32_bf16 v[94:97], v[160:163], v[232:235], v[94:97]
	v_mfma_f32_16x16x32_bf16 v[90:93], v[168:171], v[232:235], v[90:93]
	v_mfma_f32_16x16x32_bf16 v[78:81], v[160:163], v[240:243], v[78:81]
	v_mfma_f32_16x16x32_bf16 v[74:77], v[168:171], v[240:243], v[74:77]
	s_setprio 0
	s_setprio 1
	v_mfma_f32_16x16x32_bf16 v[118:121], v[172:175], v[212:215], 0
	v_mfma_f32_16x16x32_bf16 v[114:117], v[180:183], v[212:215], 0
	v_mfma_f32_16x16x32_bf16 v[102:105], v[172:175], v[220:223], 0
	v_mfma_f32_16x16x32_bf16 v[98:101], v[180:183], v[220:223], 0
	v_mfma_f32_16x16x32_bf16 v[86:89], v[172:175], v[228:231], 0
	v_mfma_f32_16x16x32_bf16 v[82:85], v[180:183], v[228:231], 0
	v_mfma_f32_16x16x32_bf16 v[70:73], v[172:175], v[236:239], 0
	v_mfma_f32_16x16x32_bf16 v[66:69], v[180:183], v[236:239], 0
	v_mfma_f32_16x16x32_bf16 v[118:121], v[176:179], v[216:219], v[118:121]
	v_mfma_f32_16x16x32_bf16 v[114:117], v[208:211], v[216:219], v[114:117]
	v_mfma_f32_16x16x32_bf16 v[102:105], v[176:179], v[224:227], v[102:105]
	v_mfma_f32_16x16x32_bf16 v[98:101], v[208:211], v[224:227], v[98:101]
	v_mfma_f32_16x16x32_bf16 v[86:89], v[176:179], v[232:235], v[86:89]
	v_mfma_f32_16x16x32_bf16 v[82:85], v[208:211], v[232:235], v[82:85]
	v_mfma_f32_16x16x32_bf16 v[70:73], v[176:179], v[240:243], v[70:73]
	v_mfma_f32_16x16x32_bf16 v[66:69], v[208:211], v[240:243], v[66:69]
	s_setprio 0
	s_barrier
	s_add_i32 s71, s71, s80
	v_lshl_add_u64 v[202:203], s[34:35], 0, v[132:133]
	s_mov_b32 m0, s71
	ds_read_b128 v[212:215], v154 offset:16384
	ds_read_b128 v[216:219], v154 offset:17408
	ds_read_b128 v[220:223], v154 offset:18432
	ds_read_b128 v[224:227], v154 offset:19456
	ds_read_b128 v[228:231], v154 offset:20480
	ds_read_b128 v[232:235], v154 offset:21504
	ds_read_b128 v[236:239], v154 offset:22528
	ds_read_b128 v[240:243], v154 offset:23552
	global_load_lds_dwordx4 v[202:203], off
	s_add_i32 m0, s71, 0x2000
	s_add_u32 s72, s34, 0x40000
	v_lshl_add_u64 v[204:205], s[34:35], 0, v[130:131]
	s_addc_u32 s73, s35, 0
	s_add_i32 s71, s74, s80
	global_load_lds_dwordx4 v[204:205], off
	v_lshl_add_u64 v[244:245], s[72:73], 0, v[132:133]
	s_mov_b32 m0, s71
	v_lshl_add_u64 v[246:247], s[40:41], 0, v[130:131]
	global_load_lds_dwordx4 v[244:245], off
	v_lshl_add_u64 v[244:245], s[72:73], 0, v[130:131]
	s_add_i32 m0, s71, 0x2000
	s_nop 0
	global_load_lds_dwordx4 v[244:245], off
	v_lshl_add_u64 v[244:245], s[40:41], 0, v[132:133]
	s_mov_b32 m0, s29
	s_nop 0
	global_load_lds_dwordx4 v[244:245], off
	s_mov_b32 m0, s81
	s_nop 0
	global_load_lds_dwordx4 v[246:247], off
	s_waitcnt vmcnt(8)
	s_waitcnt lgkmcnt(0)
	s_barrier
	s_setprio 1
	s_waitcnt lgkmcnt(0)
	v_mfma_f32_16x16x32_bf16 v[62:65], v[156:159], v[212:215], 0
	v_mfma_f32_16x16x32_bf16 v[58:61], v[164:167], v[212:215], 0
	v_mfma_f32_16x16x32_bf16 v[46:49], v[156:159], v[220:223], 0
	v_mfma_f32_16x16x32_bf16 v[42:45], v[164:167], v[220:223], 0
	v_mfma_f32_16x16x32_bf16 v[30:33], v[156:159], v[228:231], 0
	v_mfma_f32_16x16x32_bf16 v[26:29], v[164:167], v[228:231], 0
	v_mfma_f32_16x16x32_bf16 v[14:17], v[156:159], v[236:239], 0
	v_mfma_f32_16x16x32_bf16 v[10:13], v[164:167], v[236:239], 0
	v_mfma_f32_16x16x32_bf16 v[62:65], v[160:163], v[216:219], v[62:65]
	v_mfma_f32_16x16x32_bf16 v[58:61], v[168:171], v[216:219], v[58:61]
	v_mfma_f32_16x16x32_bf16 v[46:49], v[160:163], v[224:227], v[46:49]
	v_mfma_f32_16x16x32_bf16 v[42:45], v[168:171], v[224:227], v[42:45]
	v_mfma_f32_16x16x32_bf16 v[30:33], v[160:163], v[232:235], v[30:33]
	v_mfma_f32_16x16x32_bf16 v[26:29], v[168:171], v[232:235], v[26:29]
	v_mfma_f32_16x16x32_bf16 v[14:17], v[160:163], v[240:243], v[14:17]
	v_mfma_f32_16x16x32_bf16 v[10:13], v[168:171], v[240:243], v[10:13]
	s_setprio 0
	s_setprio 1
	v_mfma_f32_16x16x32_bf16 v[54:57], v[172:175], v[212:215], 0
	v_mfma_f32_16x16x32_bf16 v[50:53], v[180:183], v[212:215], 0
	v_mfma_f32_16x16x32_bf16 v[38:41], v[172:175], v[220:223], 0
	v_mfma_f32_16x16x32_bf16 v[34:37], v[180:183], v[220:223], 0
	v_mfma_f32_16x16x32_bf16 v[22:25], v[172:175], v[228:231], 0
	v_mfma_f32_16x16x32_bf16 v[18:21], v[180:183], v[228:231], 0
	v_mfma_f32_16x16x32_bf16 v[6:9], v[172:175], v[236:239], 0
	v_mfma_f32_16x16x32_bf16 v[2:5], v[180:183], v[236:239], 0
	v_mfma_f32_16x16x32_bf16 v[54:57], v[176:179], v[216:219], v[54:57]
	v_mfma_f32_16x16x32_bf16 v[50:53], v[208:211], v[216:219], v[50:53]
	v_mfma_f32_16x16x32_bf16 v[38:41], v[176:179], v[224:227], v[38:41]
	v_mfma_f32_16x16x32_bf16 v[34:37], v[208:211], v[224:227], v[34:37]
	v_mfma_f32_16x16x32_bf16 v[22:25], v[176:179], v[232:235], v[22:25]
	v_mfma_f32_16x16x32_bf16 v[18:21], v[208:211], v[232:235], v[18:21]
	v_mfma_f32_16x16x32_bf16 v[6:9], v[176:179], v[240:243], v[6:9]
	v_mfma_f32_16x16x32_bf16 v[2:5], v[208:211], v[240:243], v[2:5]
	s_setprio 0
	s_barrier
; #define PG8_STAGE(bufoff, gbase, voff) do { _Pragma("unroll") for (int _i = 0; _i < 2; ++_i) \
;         __builtin_amdgcn_global_load_lds((const unsigned*)((const char*)(gbase) + (voff)[_i]), (PG8_LAS unsigned*)(lds + (bufoff) + ldsw + _i * 8192), 16, 0, 0); } while (0)
; #define PG8_LDA(dst, b, h) do { _Pragma("unroll") for (int m = 0; m < 4; ++m) _Pragma("unroll") for (int k = 0; k < 2; ++k) dst[m][k] = *(const PG8_LAS bf16x8*)(lds + PG8_SA(b, h) + aoff + m * 2048 + k * 1024); } while (0)
; #define PG8_LDB(dst, b, h) do { _Pragma("unroll") for (int n = 0; n < 2; ++n) _Pragma("unroll") for (int k = 0; k < 2; ++k) dst[n][k] = *(const PG8_LAS bf16x8*)(lds + PG8_SB(b, h) + boff + n * 2048 + k * 1024); } while (0)
; #define PG8_MMA(ai, bj, At, Bt) do { __builtin_amdgcn_s_setprio(1); _Pragma("unroll") for (int m = 0; m < 4; ++m) _Pragma("unroll") for (int n = 0; n < 2; ++n) _Pragma("unroll") for (int k = 0; k < 2; ++k) \
;         acc[ai][bj][m][n] = __builtin_amdgcn_mfma_f32_16x16x32_bf16(Bt[n][k], At[m][k], acc[ai][bj][m][n], 0, 0, 0); __builtin_amdgcn_s_setprio(0); } while (0)
; #define PG8_WAIT_V(n) asm volatile("s_waitcnt vmcnt(" #n ")" ::: "memory")
; #define PG8_WAIT_L(n) asm volatile("s_waitcnt lgkmcnt(" #n ")" ::: "memory")
; #define PG8_BAR __builtin_amdgcn_s_barrier()
; #define PG8_SCHED __builtin_amdgcn_sched_barrier(0)
; template <class Epi, class Sched, bool ALIGN_EPI = false, bool SP2 = false>
; __device__ __forceinline__ void gemm_phase(PG8_LAS unsigned char* lds, const Gemm g, const Sched& S, const Epi& E) {
;     ...
;             PG8_LDB(B0, 1, 0); PG8_LDB(B1, 1, 1); PG8_SCHED; PG8_LDA(At, 1, 0); PG8_STAGE(PG8_SA(0, 1), a2 + hstep, voffA);
;             PG8_WAIT_V(8); PG8_WAIT_L(0); PG8_BAR; PG8_MMA(0, 0, At, B0); PG8_MMA(0, 1, At, B1); PG8_BAR; PG8_SCHED;
	s_add_i32 s71, 0, 0x18000
	v_add_u32_e32 v155, s71, v145
	s_add_i32 s72, 0, 0x1c000
	ds_read_b128 v[156:159], v155
	ds_read_b128 v[160:163], v155 offset:1024
	ds_read_b128 v[164:167], v155 offset:2048
	ds_read_b128 v[168:171], v155 offset:3072
	v_add_u32_e32 v155, s72, v145
	ds_read_b128 v[172:175], v155
	ds_read_b128 v[176:179], v155 offset:1024
	ds_read_b128 v[180:183], v155 offset:2048
	ds_read_b128 v[208:211], v155 offset:3072
	s_add_u32 s40, s40, 0x40000
	s_addc_u32 s41, s41, 0
	s_mov_b32 m0, s82
	v_lshl_add_u64 v[248:249], s[40:41], 0, v[132:133]
	ds_read_b128 v[212:215], v154 offset:32768
	ds_read_b128 v[216:219], v154 offset:33792
	ds_read_b128 v[220:223], v154 offset:34816
	ds_read_b128 v[224:227], v154 offset:35840
	ds_read_b128 v[228:231], v154 offset:36864
	ds_read_b128 v[232:235], v154 offset:37888
	ds_read_b128 v[236:239], v154 offset:38912
	ds_read_b128 v[240:243], v154 offset:39936
	global_load_lds_dwordx4 v[248:249], off
	v_lshl_add_u64 v[248:249], s[40:41], 0, v[130:131]
	s_mov_b32 m0, s83
	s_nop 0
	global_load_lds_dwordx4 v[248:249], off
	s_waitcnt vmcnt(8)
	s_waitcnt lgkmcnt(0)
	s_barrier
	s_setprio 1
	s_waitcnt lgkmcnt(0)
	v_mfma_f32_16x16x32_bf16 v[126:129], v[156:159], v[212:215], v[126:129]
	v_mfma_f32_16x16x32_bf16 v[122:125], v[164:167], v[212:215], v[122:125]
	v_mfma_f32_16x16x32_bf16 v[110:113], v[156:159], v[220:223], v[110:113]
	v_mfma_f32_16x16x32_bf16 v[106:109], v[164:167], v[220:223], v[106:109]
	v_mfma_f32_16x16x32_bf16 v[94:97], v[156:159], v[228:231], v[94:97]
	v_mfma_f32_16x16x32_bf16 v[90:93], v[164:167], v[228:231], v[90:93]
	v_mfma_f32_16x16x32_bf16 v[78:81], v[156:159], v[236:239], v[78:81]
	v_mfma_f32_16x16x32_bf16 v[74:77], v[164:167], v[236:239], v[74:77]
	v_mfma_f32_16x16x32_bf16 v[126:129], v[160:163], v[216:219], v[126:129]
	v_mfma_f32_16x16x32_bf16 v[122:125], v[168:171], v[216:219], v[122:125]
	v_mfma_f32_16x16x32_bf16 v[110:113], v[160:163], v[224:227], v[110:113]
	v_mfma_f32_16x16x32_bf16 v[106:109], v[168:171], v[224:227], v[106:109]
	v_mfma_f32_16x16x32_bf16 v[94:97], v[160:163], v[232:235], v[94:97]
	v_mfma_f32_16x16x32_bf16 v[90:93], v[168:171], v[232:235], v[90:93]
	v_mfma_f32_16x16x32_bf16 v[78:81], v[160:163], v[240:243], v[78:81]
	v_mfma_f32_16x16x32_bf16 v[74:77], v[168:171], v[240:243], v[74:77]
	s_setprio 0
	s_setprio 1
	v_mfma_f32_16x16x32_bf16 v[118:121], v[172:175], v[212:215], v[118:121]
	v_mfma_f32_16x16x32_bf16 v[114:117], v[180:183], v[212:215], v[114:117]
	v_mfma_f32_16x16x32_bf16 v[102:105], v[172:175], v[220:223], v[102:105]
	v_mfma_f32_16x16x32_bf16 v[98:101], v[180:183], v[220:223], v[98:101]
	v_mfma_f32_16x16x32_bf16 v[86:89], v[172:175], v[228:231], v[86:89]
	v_mfma_f32_16x16x32_bf16 v[82:85], v[180:183], v[228:231], v[82:85]
	v_mfma_f32_16x16x32_bf16 v[70:73], v[172:175], v[236:239], v[70:73]
	v_mfma_f32_16x16x32_bf16 v[66:69], v[180:183], v[236:239], v[66:69]
	v_mfma_f32_16x16x32_bf16 v[118:121], v[176:179], v[216:219], v[118:121]
	v_mfma_f32_16x16x32_bf16 v[114:117], v[208:211], v[216:219], v[114:117]
	v_mfma_f32_16x16x32_bf16 v[102:105], v[176:179], v[224:227], v[102:105]
	v_mfma_f32_16x16x32_bf16 v[98:101], v[208:211], v[224:227], v[98:101]
	v_mfma_f32_16x16x32_bf16 v[86:89], v[176:179], v[232:235], v[86:89]
	v_mfma_f32_16x16x32_bf16 v[82:85], v[208:211], v[232:235], v[82:85]
	v_mfma_f32_16x16x32_bf16 v[70:73], v[176:179], v[240:243], v[70:73]
	v_mfma_f32_16x16x32_bf16 v[66:69], v[208:211], v[240:243], v[66:69]
	s_setprio 0
	s_barrier
; #define PG8_STAGE(bufoff, gbase, voff) do { _Pragma("unroll") for (int _i = 0; _i < 2; ++_i) \
;         __builtin_amdgcn_global_load_lds((const unsigned*)((const char*)(gbase) + (voff)[_i]), (PG8_LAS unsigned*)(lds + (bufoff) + ldsw + _i * 8192), 16, 0, 0); } while (0)
; #define PG8_LDA(dst, b, h) do { _Pragma("unroll") for (int m = 0; m < 4; ++m) _Pragma("unroll") for (int k = 0; k < 2; ++k) dst[m][k] = *(const PG8_LAS bf16x8*)(lds + PG8_SA(b, h) + aoff + m * 2048 + k * 1024); } while (0)
; #define PG8_MMA(ai, bj, At, Bt) do { __builtin_amdgcn_s_setprio(1); _Pragma("unroll") for (int m = 0; m < 4; ++m) _Pragma("unroll") for (int n = 0; n < 2; ++n) _Pragma("unroll") for (int k = 0; k < 2; ++k) \
;         acc[ai][bj][m][n] = __builtin_amdgcn_mfma_f32_16x16x32_bf16(Bt[n][k], At[m][k], acc[ai][bj][m][n], 0, 0, 0); __builtin_amdgcn_s_setprio(0); } while (0)
; #define PG8_WAIT_V(n) asm volatile("s_waitcnt vmcnt(" #n ")" ::: "memory")
; #define PG8_WAIT_L(n) asm volatile("s_waitcnt lgkmcnt(" #n ")" ::: "memory")
; #define PG8_BAR __builtin_amdgcn_s_barrier()
; #define PG8_SCHED __builtin_amdgcn_sched_barrier(0)
; template <class Epi, class Sched, bool ALIGN_EPI = false, bool SP2 = false>
; __device__ __forceinline__ void gemm_phase(PG8_LAS unsigned char* lds, const Gemm g, const Sched& S, const Epi& E) {
;     ...
;         for (int t = 0; t < nt; t += 2) {
;             const bool last = (t == nt - 2);
;             const char* a1 = cA + (size_t)(t + 1) * kstep;
;             const char* a2 = last ? nA : cA + (size_t)(t + 2) * kstep; const char* b2 = last ? nB : cB + (size_t)(t + 2) * kstep;
;             const char* a3 = a2 + kstep; const char* b3 = b2 + kstep;
;     ...
;             PG8_LDA(At, 1, 1); PG8_STAGE(PG8_SB(1, 0), b3, voffB); PG8_STAGE(PG8_SB(1, 1), b3 + hstep, voffB); PG8_STAGE(PG8_SA(1, 0), a3, voffA);
;             PG8_WAIT_V(8); PG8_WAIT_L(0); PG8_BAR; PG8_MMA(1, 0, At, B0); PG8_MMA(1, 1, At, B1); PG8_BAR; PG8_SCHED;
	s_add_i32 s40, s71, s80
	v_lshl_add_u64 v[202:203], v[202:203], 0, s[66:67]
	s_mov_b32 m0, s40
	ds_read_b128 v[212:215], v154 offset:49152
	ds_read_b128 v[216:219], v154 offset:50176
	ds_read_b128 v[220:223], v154 offset:51200
	ds_read_b128 v[224:227], v154 offset:52224
	ds_read_b128 v[228:231], v154 offset:53248
	ds_read_b128 v[232:235], v154 offset:54272
	ds_read_b128 v[236:239], v154 offset:55296
	ds_read_b128 v[240:243], v154 offset:56320
	global_load_lds_dwordx4 v[202:203], off
	s_add_i32 m0, s40, 0x2000
	s_add_u32 s34, s34, 0x40080
	v_lshl_add_u64 v[202:203], v[204:205], 0, s[66:67]
	s_addc_u32 s35, s35, 0
	s_add_i32 s40, s72, s80
	global_load_lds_dwordx4 v[202:203], off
	v_lshl_add_u64 v[202:203], s[34:35], 0, v[132:133]
	s_mov_b32 m0, s40
	s_nop 0
	global_load_lds_dwordx4 v[202:203], off
	v_lshl_add_u64 v[202:203], s[34:35], 0, v[130:131]
	s_add_i32 m0, s40, 0x2000
	s_nop 0
	global_load_lds_dwordx4 v[202:203], off
	v_lshl_add_u64 v[202:203], v[244:245], 0, s[66:67]
	s_mov_b32 m0, s84
	s_nop 0
	global_load_lds_dwordx4 v[202:203], off
	v_lshl_add_u64 v[202:203], v[246:247], 0, s[66:67]
	s_mov_b32 m0, s85
	s_nop 0
	global_load_lds_dwordx4 v[202:203], off
	s_waitcnt vmcnt(8)
	s_waitcnt lgkmcnt(0)
	s_barrier
	s_setprio 1
	s_waitcnt lgkmcnt(0)
	v_mfma_f32_16x16x32_bf16 v[62:65], v[156:159], v[212:215], v[62:65]
	v_mfma_f32_16x16x32_bf16 v[58:61], v[164:167], v[212:215], v[58:61]
	v_mfma_f32_16x16x32_bf16 v[46:49], v[156:159], v[220:223], v[46:49]
	v_mfma_f32_16x16x32_bf16 v[42:45], v[164:167], v[220:223], v[42:45]
	v_mfma_f32_16x16x32_bf16 v[30:33], v[156:159], v[228:231], v[30:33]
	v_mfma_f32_16x16x32_bf16 v[26:29], v[164:167], v[228:231], v[26:29]
	v_mfma_f32_16x16x32_bf16 v[14:17], v[156:159], v[236:239], v[14:17]
	v_mfma_f32_16x16x32_bf16 v[10:13], v[164:167], v[236:239], v[10:13]
	v_mfma_f32_16x16x32_bf16 v[62:65], v[160:163], v[216:219], v[62:65]
	v_mfma_f32_16x16x32_bf16 v[58:61], v[168:171], v[216:219], v[58:61]
	v_mfma_f32_16x16x32_bf16 v[46:49], v[160:163], v[224:227], v[46:49]
	v_mfma_f32_16x16x32_bf16 v[42:45], v[168:171], v[224:227], v[42:45]
	v_mfma_f32_16x16x32_bf16 v[30:33], v[160:163], v[232:235], v[30:33]
	v_mfma_f32_16x16x32_bf16 v[26:29], v[168:171], v[232:235], v[26:29]
	v_mfma_f32_16x16x32_bf16 v[14:17], v[160:163], v[240:243], v[14:17]
	v_mfma_f32_16x16x32_bf16 v[10:13], v[168:171], v[240:243], v[10:13]
	s_setprio 0
	s_setprio 1
	v_mfma_f32_16x16x32_bf16 v[54:57], v[172:175], v[212:215], v[54:57]
	v_mfma_f32_16x16x32_bf16 v[50:53], v[180:183], v[212:215], v[50:53]
	v_mfma_f32_16x16x32_bf16 v[38:41], v[172:175], v[220:223], v[38:41]
	v_mfma_f32_16x16x32_bf16 v[34:37], v[180:183], v[220:223], v[34:37]
	v_mfma_f32_16x16x32_bf16 v[22:25], v[172:175], v[228:231], v[22:25]
	v_mfma_f32_16x16x32_bf16 v[18:21], v[180:183], v[228:231], v[18:21]
	v_mfma_f32_16x16x32_bf16 v[6:9], v[172:175], v[236:239], v[6:9]
	v_mfma_f32_16x16x32_bf16 v[2:5], v[180:183], v[236:239], v[2:5]
	v_mfma_f32_16x16x32_bf16 v[54:57], v[176:179], v[216:219], v[54:57]
	v_mfma_f32_16x16x32_bf16 v[50:53], v[208:211], v[216:219], v[50:53]
	v_mfma_f32_16x16x32_bf16 v[38:41], v[176:179], v[224:227], v[38:41]
	v_mfma_f32_16x16x32_bf16 v[34:37], v[208:211], v[224:227], v[34:37]
	v_mfma_f32_16x16x32_bf16 v[22:25], v[176:179], v[232:235], v[22:25]
	v_mfma_f32_16x16x32_bf16 v[18:21], v[208:211], v[232:235], v[18:21]
	v_mfma_f32_16x16x32_bf16 v[6:9], v[176:179], v[240:243], v[6:9]
	v_mfma_f32_16x16x32_bf16 v[2:5], v[208:211], v[240:243], v[2:5]
	s_setprio 0
	s_barrier
	s_add_i32 s62, s62, 2
	s_add_u32 s30, s30, 0x100
	s_addc_u32 s31, s31, 0
	s_add_u32 s52, s52, 0x100
	s_addc_u32 s54, s54, 0
	s_cmp_gt_u32 s62, 13
	s_cbranch_scc0 .LBB0_163
	s_branch .Lku_exit
	s_nop 0
	s_nop 0
	s_nop 0
	s_nop 0
	s_nop 0
	s_nop 0
	s_nop 0
	s_nop 0
	s_nop 0

; #define PG8_STAGE(bufoff, gbase, voff) do { _Pragma("unroll") for (int _i = 0; _i < 2; ++_i) \
;         __builtin_amdgcn_global_load_lds((const unsigned*)((const char*)(gbase) + (voff)[_i]), (PG8_LAS unsigned*)(lds + (bufoff) + ldsw + _i * 8192), 16, 0, 0); } while (0)
; #define PG8_LDA(dst, b, h) do { _Pragma("unroll") for (int m = 0; m < 4; ++m) _Pragma("unroll") for (int k = 0; k < 2; ++k) dst[m][k] = *(const PG8_LAS bf16x8*)(lds + PG8_SA(b, h) + aoff + m * 2048 + k * 1024); } while (0)
; #define PG8_LDB(dst, b, h) do { _Pragma("unroll") for (int n = 0; n < 2; ++n) _Pragma("unroll") for (int k = 0; k < 2; ++k) dst[n][k] = *(const PG8_LAS bf16x8*)(lds + PG8_SB(b, h) + boff + n * 2048 + k * 1024); } while (0)
; #define PG8_MMA(ai, bj, At, Bt) do { __builtin_amdgcn_s_setprio(1); _Pragma("unroll") for (int m = 0; m < 4; ++m) _Pragma("unroll") for (int n = 0; n < 2; ++n) _Pragma("unroll") for (int k = 0; k < 2; ++k) \
;         acc[ai][bj][m][n] = __builtin_amdgcn_mfma_f32_16x16x32_bf16(Bt[n][k], At[m][k], acc[ai][bj][m][n], 0, 0, 0); __builtin_amdgcn_s_setprio(0); } while (0)
; #define PG8_WAIT_V(n) asm volatile("s_waitcnt vmcnt(" #n ")" ::: "memory")
; #define PG8_WAIT_L(n) asm volatile("s_waitcnt lgkmcnt(" #n ")" ::: "memory")
; #define PG8_BAR __builtin_amdgcn_s_barrier()
; template <class Epi, class Sched, bool ALIGN_EPI = false, bool SP2 = false>
; __device__ __forceinline__ void gemm_phase(PG8_LAS unsigned char* lds, const Gemm g, const Sched& S, const Epi& E) {
;     ...
;         const bool has_next = S.next(ui + 1, nxt);
;         const char* nA = has_next ? (const char*)g.A + (size_t)nxt.pm * tstep : cA; const char* nB = has_next ? (const char*)g.Bt + (size_t)nxt.pn * tstep : cB;
;         for (int t = 0; t < nt; t += 2) {
;             const bool last = (t == nt - 2);
;             const char* a1 = cA + (size_t)(t + 1) * kstep;
;             const char* a2 = last ? nA : cA + (size_t)(t + 2) * kstep; const char* b2 = last ? nB : cB + (size_t)(t + 2) * kstep;
;             const char* a3 = a2 + kstep; const char* b3 = b2 + kstep;
;             if (last && has_next) S.a_ready(nxt);
;             if constexpr (SP2) {
;             PG8_LDB(B0, 0, 0); PG8_LDB(B1, 0, 1); PG8_SCHED; PG8_LDA(At, 0, 0); PG8_STAGE(PG8_SA(1, 1), a1 + hstep, voffA);
;             PG8_WAIT_V(8); PG8_WAIT_L(0); PG8_BAR; PG8_MMA(0, 0, At, B0); PG8_MMA(0, 1, At, B1); PG8_BAR; PG8_SCHED;
.LBB0_187:
	s_ashr_i32 s23, s22, 31
	s_lshl_b64 s[24:25], s[22:23], 19
	s_add_u32 s24, s49, s24
	s_addc_u32 s25, s74, s25
	s_and_b64 s[26:27], s[8:9], exec
	s_cselect_b32 s23, s25, s31
	s_cselect_b32 s54, s24, s30
	s_ashr_i32 s21, s20, 31
	s_lshl_b64 s[26:27], s[20:21], 19
	s_add_u32 s26, s72, s26
	s_addc_u32 s27, s75, s27
	s_and_b64 s[40:41], s[8:9], exec
	s_cselect_b32 s21, s27, s35
	s_cselect_b32 s62, s26, s34
	s_add_u32 s30, s30, 0x40080
	s_addc_u32 s31, s31, 0
	s_add_u32 s64, s34, 0x100
	v_mov_b32_e32 v2, 0
	s_addc_u32 s71, s35, 0
	s_mov_b32 s85, -2
	s_add_u32 s34, s30, 0xfffc0080
	s_addc_u32 s35, s31, -1
	s_add_i32 s86, 0, 0x10000
	s_cmp_eq_u32 s85, 12
	s_cselect_b32 s41, s23, s35
	s_cselect_b32 s40, s54, s34
	v_add_u32_e32 v0, s86, v143
	s_cselect_b32 s35, s21, s71
	s_cselect_b32 s34, s62, s64
	s_add_i32 s88, 0, 0x14000
	ds_read_b128 v[152:155], v0
	ds_read_b128 v[156:159], v0 offset:1024
	ds_read_b128 v[160:163], v0 offset:2048
	ds_read_b128 v[164:167], v0 offset:3072
	v_add_u32_e32 v0, s88, v143
	ds_read_b128 v[168:171], v0
	ds_read_b128 v[172:175], v0 offset:1024
	ds_read_b128 v[176:179], v0 offset:2048
	ds_read_b128 v[180:183], v0 offset:3072
	v_lshl_add_u64 v[242:243], s[30:31], 0, v[148:149]
	s_add_i32 m0, s50, 0xc000
	ds_read_b128 v[202:205], v212
	ds_read_b128 v[214:217], v212 offset:1024
	ds_read_b128 v[218:221], v212 offset:2048
	ds_read_b128 v[222:225], v212 offset:3072
	ds_read_b128 v[226:229], v212 offset:4096
	ds_read_b128 v[230:233], v212 offset:5120
	ds_read_b128 v[234:237], v212 offset:6144
	ds_read_b128 v[238:241], v212 offset:7168
	global_load_lds_dwordx4 v[242:243], off
	v_lshl_add_u64 v[242:243], s[30:31], 0, v[150:151]
	s_add_i32 m0, s50, 0xe000
	s_nop 0
	global_load_lds_dwordx4 v[242:243], off
	s_waitcnt vmcnt(8)
	s_waitcnt lgkmcnt(0)
	s_barrier
	s_setprio 1
	s_waitcnt lgkmcnt(0)
	v_mfma_f32_16x16x32_bf16 v[126:129], v[152:155], v[202:205], 0
	v_mfma_f32_16x16x32_bf16 v[122:125], v[160:163], v[202:205], 0
	v_mfma_f32_16x16x32_bf16 v[110:113], v[152:155], v[218:221], 0
	v_mfma_f32_16x16x32_bf16 v[106:109], v[160:163], v[218:221], 0
	v_mfma_f32_16x16x32_bf16 v[94:97], v[152:155], v[226:229], 0
	v_mfma_f32_16x16x32_bf16 v[90:93], v[160:163], v[226:229], 0
	v_mfma_f32_16x16x32_bf16 v[78:81], v[152:155], v[234:237], 0
	v_mfma_f32_16x16x32_bf16 v[74:77], v[160:163], v[234:237], 0
	v_mfma_f32_16x16x32_bf16 v[126:129], v[156:159], v[214:217], v[126:129]
	v_mfma_f32_16x16x32_bf16 v[122:125], v[164:167], v[214:217], v[122:125]
	v_mfma_f32_16x16x32_bf16 v[110:113], v[156:159], v[222:225], v[110:113]
	v_mfma_f32_16x16x32_bf16 v[106:109], v[164:167], v[222:225], v[106:109]
	v_mfma_f32_16x16x32_bf16 v[94:97], v[156:159], v[230:233], v[94:97]
	v_mfma_f32_16x16x32_bf16 v[90:93], v[164:167], v[230:233], v[90:93]
	v_mfma_f32_16x16x32_bf16 v[78:81], v[156:159], v[238:241], v[78:81]
	v_mfma_f32_16x16x32_bf16 v[74:77], v[164:167], v[238:241], v[74:77]
	s_setprio 0
	s_setprio 1
	v_mfma_f32_16x16x32_bf16 v[118:121], v[168:171], v[202:205], 0
	v_mfma_f32_16x16x32_bf16 v[114:117], v[176:179], v[202:205], 0
	v_mfma_f32_16x16x32_bf16 v[102:105], v[168:171], v[218:221], 0
	v_mfma_f32_16x16x32_bf16 v[98:101], v[176:179], v[218:221], 0
	v_mfma_f32_16x16x32_bf16 v[86:89], v[168:171], v[226:229], 0
	v_mfma_f32_16x16x32_bf16 v[82:85], v[176:179], v[226:229], 0
	v_mfma_f32_16x16x32_bf16 v[70:73], v[168:171], v[234:237], 0
	v_mfma_f32_16x16x32_bf16 v[66:69], v[176:179], v[234:237], 0
	v_mfma_f32_16x16x32_bf16 v[118:121], v[172:175], v[214:217], v[118:121]
	v_mfma_f32_16x16x32_bf16 v[114:117], v[180:183], v[214:217], v[114:117]
	v_mfma_f32_16x16x32_bf16 v[102:105], v[172:175], v[222:225], v[102:105]
	v_mfma_f32_16x16x32_bf16 v[98:101], v[180:183], v[222:225], v[98:101]
	v_mfma_f32_16x16x32_bf16 v[86:89], v[172:175], v[230:233], v[86:89]
	v_mfma_f32_16x16x32_bf16 v[82:85], v[180:183], v[230:233], v[82:85]
	v_mfma_f32_16x16x32_bf16 v[70:73], v[172:175], v[238:241], v[70:73]
	v_mfma_f32_16x16x32_bf16 v[66:69], v[180:183], v[238:241], v[66:69]
	s_setprio 0
	s_barrier
	s_add_i32 s86, s86, s46
	v_lshl_add_u64 v[242:243], s[34:35], 0, v[132:133]
	s_mov_b32 m0, s86
	ds_read_b128 v[202:205], v212 offset:16384
	ds_read_b128 v[214:217], v212 offset:17408
	ds_read_b128 v[218:221], v212 offset:18432
	ds_read_b128 v[222:225], v212 offset:19456
	ds_read_b128 v[226:229], v212 offset:20480
	ds_read_b128 v[230:233], v212 offset:21504
	ds_read_b128 v[234:237], v212 offset:22528
	ds_read_b128 v[238:241], v212 offset:23552
	global_load_lds_dwordx4 v[242:243], off
	s_add_i32 m0, s86, 0x2000
	s_add_u32 s86, s34, 0x40000
	v_lshl_add_u64 v[244:245], s[34:35], 0, v[130:131]
	s_addc_u32 s87, s35, 0
	s_add_i32 s88, s88, s46
	global_load_lds_dwordx4 v[244:245], off
	v_lshl_add_u64 v[246:247], s[86:87], 0, v[132:133]
	s_mov_b32 m0, s88
	v_lshl_add_u64 v[248:249], s[40:41], 0, v[130:131]
	global_load_lds_dwordx4 v[246:247], off
	v_lshl_add_u64 v[246:247], s[86:87], 0, v[130:131]
	s_add_i32 m0, s88, 0x2000
	s_nop 0
	global_load_lds_dwordx4 v[246:247], off
	v_lshl_add_u64 v[246:247], s[40:41], 0, v[132:133]
	s_mov_b32 m0, s50
	s_nop 0
	global_load_lds_dwordx4 v[246:247], off
	s_mov_b32 m0, s73
	s_nop 0
	global_load_lds_dwordx4 v[248:249], off
	s_waitcnt vmcnt(8)
	s_waitcnt lgkmcnt(0)
	s_barrier
; #define PG8_STAGE(bufoff, gbase, voff) do { _Pragma("unroll") for (int _i = 0; _i < 2; ++_i) \
;         __builtin_amdgcn_global_load_lds((const unsigned*)((const char*)(gbase) + (voff)[_i]), (PG8_LAS unsigned*)(lds + (bufoff) + ldsw + _i * 8192), 16, 0, 0); } while (0)
; #define PG8_LDA(dst, b, h) do { _Pragma("unroll") for (int m = 0; m < 4; ++m) _Pragma("unroll") for (int k = 0; k < 2; ++k) dst[m][k] = *(const PG8_LAS bf16x8*)(lds + PG8_SA(b, h) + aoff + m * 2048 + k * 1024); } while (0)
; #define PG8_LDB(dst, b, h) do { _Pragma("unroll") for (int n = 0; n < 2; ++n) _Pragma("unroll") for (int k = 0; k < 2; ++k) dst[n][k] = *(const PG8_LAS bf16x8*)(lds + PG8_SB(b, h) + boff + n * 2048 + k * 1024); } while (0)
; #define PG8_MMA(ai, bj, At, Bt) do { __builtin_amdgcn_s_setprio(1); _Pragma("unroll") for (int m = 0; m < 4; ++m) _Pragma("unroll") for (int n = 0; n < 2; ++n) _Pragma("unroll") for (int k = 0; k < 2; ++k) \
;         acc[ai][bj][m][n] = __builtin_amdgcn_mfma_f32_16x16x32_bf16(Bt[n][k], At[m][k], acc[ai][bj][m][n], 0, 0, 0); __builtin_amdgcn_s_setprio(0); } while (0)
; #define PG8_WAIT_V(n) asm volatile("s_waitcnt vmcnt(" #n ")" ::: "memory")
; #define PG8_WAIT_L(n) asm volatile("s_waitcnt lgkmcnt(" #n ")" ::: "memory")
; #define PG8_BAR __builtin_amdgcn_s_barrier()
; #define PG8_SCHED __builtin_amdgcn_sched_barrier(0)
; template <class Epi, class Sched, bool ALIGN_EPI = false, bool SP2 = false>
; __device__ __forceinline__ void gemm_phase(PG8_LAS unsigned char* lds, const Gemm g, const Sched& S, const Epi& E) {
;     ...
;             PG8_WAIT_V(8); PG8_WAIT_L(0); PG8_BAR; PG8_MMA(0, 0, At, B0); PG8_MMA(0, 1, At, B1); PG8_BAR; PG8_SCHED;
;             PG8_LDA(At, 0, 1); PG8_STAGE(PG8_SB(0, 0), b2, voffB); PG8_STAGE(PG8_SB(0, 1), b2 + hstep, voffB); PG8_STAGE(PG8_SA(0, 0), a2, voffA);
;             PG8_WAIT_V(8); PG8_WAIT_L(0); PG8_BAR; PG8_MMA(1, 0, At, B0); PG8_MMA(1, 1, At, B1); PG8_BAR; PG8_SCHED;
;             PG8_LDB(B0, 1, 0); PG8_LDB(B1, 1, 1); PG8_SCHED; PG8_LDA(At, 1, 0); PG8_STAGE(PG8_SA(0, 1), a2 + hstep, voffA);
;             PG8_WAIT_V(8); PG8_WAIT_L(0); PG8_BAR; PG8_MMA(0, 0, At, B0); PG8_MMA(0, 1, At, B1); PG8_BAR; PG8_SCHED;
	s_setprio 1
	s_waitcnt lgkmcnt(0)
	v_mfma_f32_16x16x32_bf16 v[62:65], v[152:155], v[202:205], 0
	v_mfma_f32_16x16x32_bf16 v[58:61], v[160:163], v[202:205], 0
	v_mfma_f32_16x16x32_bf16 v[46:49], v[152:155], v[218:221], 0
	v_mfma_f32_16x16x32_bf16 v[42:45], v[160:163], v[218:221], 0
	v_mfma_f32_16x16x32_bf16 v[30:33], v[152:155], v[226:229], 0
	v_mfma_f32_16x16x32_bf16 v[26:29], v[160:163], v[226:229], 0
	v_mfma_f32_16x16x32_bf16 v[14:17], v[152:155], v[234:237], 0
	v_mfma_f32_16x16x32_bf16 v[10:13], v[160:163], v[234:237], 0
	v_mfma_f32_16x16x32_bf16 v[62:65], v[156:159], v[214:217], v[62:65]
	v_mfma_f32_16x16x32_bf16 v[58:61], v[164:167], v[214:217], v[58:61]
	v_mfma_f32_16x16x32_bf16 v[46:49], v[156:159], v[222:225], v[46:49]
	v_mfma_f32_16x16x32_bf16 v[42:45], v[164:167], v[222:225], v[42:45]
	v_mfma_f32_16x16x32_bf16 v[30:33], v[156:159], v[230:233], v[30:33]
	v_mfma_f32_16x16x32_bf16 v[26:29], v[164:167], v[230:233], v[26:29]
	v_mfma_f32_16x16x32_bf16 v[14:17], v[156:159], v[238:241], v[14:17]
	v_mfma_f32_16x16x32_bf16 v[10:13], v[164:167], v[238:241], v[10:13]
	s_setprio 0
	s_setprio 1
	v_mfma_f32_16x16x32_bf16 v[54:57], v[168:171], v[202:205], 0
	v_mfma_f32_16x16x32_bf16 v[50:53], v[176:179], v[202:205], 0
	v_mfma_f32_16x16x32_bf16 v[38:41], v[168:171], v[218:221], 0
	v_mfma_f32_16x16x32_bf16 v[34:37], v[176:179], v[218:221], 0
	v_mfma_f32_16x16x32_bf16 v[22:25], v[168:171], v[226:229], 0
	v_mfma_f32_16x16x32_bf16 v[18:21], v[176:179], v[226:229], 0
	v_mfma_f32_16x16x32_bf16 v[6:9], v[168:171], v[234:237], 0
	v_mfma_f32_16x16x32_bf16 v[2:5], v[176:179], v[234:237], 0
	v_mfma_f32_16x16x32_bf16 v[54:57], v[172:175], v[214:217], v[54:57]
	v_mfma_f32_16x16x32_bf16 v[50:53], v[180:183], v[214:217], v[50:53]
	v_mfma_f32_16x16x32_bf16 v[38:41], v[172:175], v[222:225], v[38:41]
	v_mfma_f32_16x16x32_bf16 v[34:37], v[180:183], v[222:225], v[34:37]
	v_mfma_f32_16x16x32_bf16 v[22:25], v[172:175], v[230:233], v[22:25]
	v_mfma_f32_16x16x32_bf16 v[18:21], v[180:183], v[230:233], v[18:21]
	v_mfma_f32_16x16x32_bf16 v[6:9], v[172:175], v[238:241], v[6:9]
	v_mfma_f32_16x16x32_bf16 v[2:5], v[180:183], v[238:241], v[2:5]
	s_setprio 0
	s_barrier
	s_add_i32 s86, 0, 0x18000
	v_add_u32_e32 v0, s86, v143
	s_add_i32 s87, 0, 0x1c000
	ds_read_b128 v[152:155], v0
	ds_read_b128 v[156:159], v0 offset:1024
	ds_read_b128 v[160:163], v0 offset:2048
	ds_read_b128 v[164:167], v0 offset:3072
	v_add_u32_e32 v0, s87, v143
	ds_read_b128 v[168:171], v0
	ds_read_b128 v[172:175], v0 offset:1024
	ds_read_b128 v[176:179], v0 offset:2048
	ds_read_b128 v[180:183], v0 offset:3072
	s_add_u32 s40, s40, 0x40000
	s_addc_u32 s41, s41, 0
	s_mov_b32 m0, s77
	v_lshl_add_u64 v[250:251], s[40:41], 0, v[132:133]
	ds_read_b128 v[202:205], v212 offset:32768
	ds_read_b128 v[214:217], v212 offset:33792
	ds_read_b128 v[218:221], v212 offset:34816
	ds_read_b128 v[222:225], v212 offset:35840
	ds_read_b128 v[226:229], v212 offset:36864
	ds_read_b128 v[230:233], v212 offset:37888
	ds_read_b128 v[234:237], v212 offset:38912
	ds_read_b128 v[238:241], v212 offset:39936
	global_load_lds_dwordx4 v[250:251], off
	v_lshl_add_u64 v[250:251], s[40:41], 0, v[130:131]
	s_mov_b32 m0, s78
	s_nop 0
	global_load_lds_dwordx4 v[250:251], off
	s_waitcnt vmcnt(8)
	s_waitcnt lgkmcnt(0)
	s_barrier
	s_setprio 1
	s_waitcnt lgkmcnt(0)
	v_mfma_f32_16x16x32_bf16 v[126:129], v[152:155], v[202:205], v[126:129]
	v_mfma_f32_16x16x32_bf16 v[122:125], v[160:163], v[202:205], v[122:125]
	v_mfma_f32_16x16x32_bf16 v[110:113], v[152:155], v[218:221], v[110:113]
	v_mfma_f32_16x16x32_bf16 v[106:109], v[160:163], v[218:221], v[106:109]
	v_mfma_f32_16x16x32_bf16 v[94:97], v[152:155], v[226:229], v[94:97]
	v_mfma_f32_16x16x32_bf16 v[90:93], v[160:163], v[226:229], v[90:93]
	v_mfma_f32_16x16x32_bf16 v[78:81], v[152:155], v[234:237], v[78:81]
	v_mfma_f32_16x16x32_bf16 v[74:77], v[160:163], v[234:237], v[74:77]
	v_mfma_f32_16x16x32_bf16 v[126:129], v[156:159], v[214:217], v[126:129]
	v_mfma_f32_16x16x32_bf16 v[122:125], v[164:167], v[214:217], v[122:125]
	v_mfma_f32_16x16x32_bf16 v[110:113], v[156:159], v[222:225], v[110:113]
	v_mfma_f32_16x16x32_bf16 v[106:109], v[164:167], v[222:225], v[106:109]
	v_mfma_f32_16x16x32_bf16 v[94:97], v[156:159], v[230:233], v[94:97]
	v_mfma_f32_16x16x32_bf16 v[90:93], v[164:167], v[230:233], v[90:93]
	v_mfma_f32_16x16x32_bf16 v[78:81], v[156:159], v[238:241], v[78:81]
	v_mfma_f32_16x16x32_bf16 v[74:77], v[164:167], v[238:241], v[74:77]
	s_setprio 0
	s_setprio 1
	v_mfma_f32_16x16x32_bf16 v[118:121], v[168:171], v[202:205], v[118:121]
	v_mfma_f32_16x16x32_bf16 v[114:117], v[176:179], v[202:205], v[114:117]
	v_mfma_f32_16x16x32_bf16 v[102:105], v[168:171], v[218:221], v[102:105]
	v_mfma_f32_16x16x32_bf16 v[98:101], v[176:179], v[218:221], v[98:101]
	v_mfma_f32_16x16x32_bf16 v[86:89], v[168:171], v[226:229], v[86:89]
	v_mfma_f32_16x16x32_bf16 v[82:85], v[176:179], v[226:229], v[82:85]
	v_mfma_f32_16x16x32_bf16 v[70:73], v[168:171], v[234:237], v[70:73]
	v_mfma_f32_16x16x32_bf16 v[66:69], v[176:179], v[234:237], v[66:69]
	v_mfma_f32_16x16x32_bf16 v[118:121], v[172:175], v[214:217], v[118:121]
	v_mfma_f32_16x16x32_bf16 v[114:117], v[180:183], v[214:217], v[114:117]
	v_mfma_f32_16x16x32_bf16 v[102:105], v[172:175], v[222:225], v[102:105]
	v_mfma_f32_16x16x32_bf16 v[98:101], v[180:183], v[222:225], v[98:101]
	v_mfma_f32_16x16x32_bf16 v[86:89], v[172:175], v[230:233], v[86:89]
	v_mfma_f32_16x16x32_bf16 v[82:85], v[180:183], v[230:233], v[82:85]
	v_mfma_f32_16x16x32_bf16 v[70:73], v[172:175], v[238:241], v[70:73]
	v_mfma_f32_16x16x32_bf16 v[66:69], v[180:183], v[238:241], v[66:69]
	s_setprio 0
	s_barrier
; #define PG8_STAGE(bufoff, gbase, voff) do { _Pragma("unroll") for (int _i = 0; _i < 2; ++_i) \
;         __builtin_amdgcn_global_load_lds((const unsigned*)((const char*)(gbase) + (voff)[_i]), (PG8_LAS unsigned*)(lds + (bufoff) + ldsw + _i * 8192), 16, 0, 0); } while (0)
; #define PG8_LDA(dst, b, h) do { _Pragma("unroll") for (int m = 0; m < 4; ++m) _Pragma("unroll") for (int k = 0; k < 2; ++k) dst[m][k] = *(const PG8_LAS bf16x8*)(lds + PG8_SA(b, h) + aoff + m * 2048 + k * 1024); } while (0)
; #define PG8_MMA(ai, bj, At, Bt) do { __builtin_amdgcn_s_setprio(1); _Pragma("unroll") for (int m = 0; m < 4; ++m) _Pragma("unroll") for (int n = 0; n < 2; ++n) _Pragma("unroll") for (int k = 0; k < 2; ++k) \
;         acc[ai][bj][m][n] = __builtin_amdgcn_mfma_f32_16x16x32_bf16(Bt[n][k], At[m][k], acc[ai][bj][m][n], 0, 0, 0); __builtin_amdgcn_s_setprio(0); } while (0)
; #define PG8_WAIT_V(n) asm volatile("s_waitcnt vmcnt(" #n ")" ::: "memory")
; #define PG8_WAIT_L(n) asm volatile("s_waitcnt lgkmcnt(" #n ")" ::: "memory")
; #define PG8_BAR __builtin_amdgcn_s_barrier()
; #define PG8_SCHED __builtin_amdgcn_sched_barrier(0)
; template <class Epi, class Sched, bool ALIGN_EPI = false, bool SP2 = false>
; __device__ __forceinline__ void gemm_phase(PG8_LAS unsigned char* lds, const Gemm g, const Sched& S, const Epi& E) {
;     ...
;             PG8_LDA(At, 1, 1); PG8_STAGE(PG8_SB(1, 0), b3, voffB); PG8_STAGE(PG8_SB(1, 1), b3 + hstep, voffB); PG8_STAGE(PG8_SA(1, 0), a3, voffA);
;             PG8_WAIT_V(8); PG8_WAIT_L(0); PG8_BAR; PG8_MMA(1, 0, At, B0); PG8_MMA(1, 1, At, B1); PG8_BAR; PG8_SCHED;
	s_add_i32 s40, s86, s46
	v_lshl_add_u64 v[242:243], v[242:243], 0, s[66:67]
	s_mov_b32 m0, s40
	ds_read_b128 v[202:205], v212 offset:49152
	ds_read_b128 v[214:217], v212 offset:50176
	ds_read_b128 v[218:221], v212 offset:51200
	ds_read_b128 v[222:225], v212 offset:52224
	ds_read_b128 v[226:229], v212 offset:53248
	ds_read_b128 v[230:233], v212 offset:54272
	ds_read_b128 v[234:237], v212 offset:55296
	ds_read_b128 v[238:241], v212 offset:56320
	global_load_lds_dwordx4 v[242:243], off
	s_add_i32 m0, s40, 0x2000
	s_add_u32 s34, s34, 0x40080
	v_lshl_add_u64 v[242:243], v[244:245], 0, s[66:67]
	s_addc_u32 s35, s35, 0
	s_add_i32 s40, s87, s46
	global_load_lds_dwordx4 v[242:243], off
	v_lshl_add_u64 v[242:243], s[34:35], 0, v[132:133]
	s_mov_b32 m0, s40
	s_nop 0
	global_load_lds_dwordx4 v[242:243], off
	v_lshl_add_u64 v[242:243], s[34:35], 0, v[130:131]
	s_add_i32 m0, s40, 0x2000
	s_nop 0
	global_load_lds_dwordx4 v[242:243], off
	v_lshl_add_u64 v[242:243], v[246:247], 0, s[66:67]
	s_mov_b32 m0, s83
	s_nop 0
	global_load_lds_dwordx4 v[242:243], off
	v_lshl_add_u64 v[242:243], v[248:249], 0, s[66:67]
	s_mov_b32 m0, s84
	s_nop 0
	global_load_lds_dwordx4 v[242:243], off
	s_waitcnt vmcnt(8)
	s_waitcnt lgkmcnt(0)
	s_barrier
	s_setprio 1
	s_waitcnt lgkmcnt(0)
	v_mfma_f32_16x16x32_bf16 v[62:65], v[152:155], v[202:205], v[62:65]
	v_mfma_f32_16x16x32_bf16 v[58:61], v[160:163], v[202:205], v[58:61]
	v_mfma_f32_16x16x32_bf16 v[46:49], v[152:155], v[218:221], v[46:49]
	v_mfma_f32_16x16x32_bf16 v[42:45], v[160:163], v[218:221], v[42:45]
	v_mfma_f32_16x16x32_bf16 v[30:33], v[152:155], v[226:229], v[30:33]
	v_mfma_f32_16x16x32_bf16 v[26:29], v[160:163], v[226:229], v[26:29]
	v_mfma_f32_16x16x32_bf16 v[14:17], v[152:155], v[234:237], v[14:17]
	v_mfma_f32_16x16x32_bf16 v[10:13], v[160:163], v[234:237], v[10:13]
	v_mfma_f32_16x16x32_bf16 v[62:65], v[156:159], v[214:217], v[62:65]
	v_mfma_f32_16x16x32_bf16 v[58:61], v[164:167], v[214:217], v[58:61]
	v_mfma_f32_16x16x32_bf16 v[46:49], v[156:159], v[222:225], v[46:49]
	v_mfma_f32_16x16x32_bf16 v[42:45], v[164:167], v[222:225], v[42:45]
	v_mfma_f32_16x16x32_bf16 v[30:33], v[156:159], v[230:233], v[30:33]
	v_mfma_f32_16x16x32_bf16 v[26:29], v[164:167], v[230:233], v[26:29]
	v_mfma_f32_16x16x32_bf16 v[14:17], v[156:159], v[238:241], v[14:17]
	v_mfma_f32_16x16x32_bf16 v[10:13], v[164:167], v[238:241], v[10:13]
	s_setprio 0
	s_setprio 1
	v_mfma_f32_16x16x32_bf16 v[54:57], v[168:171], v[202:205], v[54:57]
	v_mfma_f32_16x16x32_bf16 v[50:53], v[176:179], v[202:205], v[50:53]
	v_mfma_f32_16x16x32_bf16 v[38:41], v[168:171], v[218:221], v[38:41]
	v_mfma_f32_16x16x32_bf16 v[34:37], v[176:179], v[218:221], v[34:37]
	v_mfma_f32_16x16x32_bf16 v[22:25], v[168:171], v[226:229], v[22:25]
	v_mfma_f32_16x16x32_bf16 v[18:21], v[176:179], v[226:229], v[18:21]
	v_mfma_f32_16x16x32_bf16 v[6:9], v[168:171], v[234:237], v[6:9]
	v_mfma_f32_16x16x32_bf16 v[2:5], v[176:179], v[234:237], v[2:5]
	v_mfma_f32_16x16x32_bf16 v[54:57], v[172:175], v[214:217], v[54:57]
	v_mfma_f32_16x16x32_bf16 v[50:53], v[180:183], v[214:217], v[50:53]
	v_mfma_f32_16x16x32_bf16 v[38:41], v[172:175], v[222:225], v[38:41]
	v_mfma_f32_16x16x32_bf16 v[34:37], v[180:183], v[222:225], v[34:37]
	v_mfma_f32_16x16x32_bf16 v[22:25], v[172:175], v[230:233], v[22:25]
	v_mfma_f32_16x16x32_bf16 v[18:21], v[180:183], v[230:233], v[18:21]
	v_mfma_f32_16x16x32_bf16 v[6:9], v[172:175], v[238:241], v[6:9]
	v_mfma_f32_16x16x32_bf16 v[2:5], v[180:183], v[238:241], v[2:5]
	s_setprio 0
	s_barrier
	s_add_i32 s85, s85, 2
	s_add_u32 s30, s30, 0x100
	s_addc_u32 s31, s31, 0
	s_add_u32 s64, s64, 0x100
	s_addc_u32 s71, s71, 0
	s_cmp_gt_u32 s85, 13
	s_cbranch_scc0 .LBB0_188
	s_branch .Lpeel_o_exit
	s_nop 0
	s_nop 0

; #define PG8_BAR __builtin_amdgcn_s_barrier()
; template <class Epi, class Sched, bool ALIGN_EPI = false, bool SP2 = false>
; __device__ __forceinline__ void gemm_phase(PG8_LAS unsigned char* lds, const Gemm g, const Sched& S, const Epi& E) {
;     ...
;         }
;         if constexpr (ALIGN_EPI) { if (wr == 0) PG8_BAR; }
;         if constexpr (!Epi::AFTER_DRAIN) { E(acc, cur, wr, wc, fr, fq); S.done(cur); }
;         if (!has_next) break;
.Lpeel_o_exit:
	s_and_b64 vcc, exec, s[18:19]
	s_cbranch_vccz .LBB0_191
	s_barrier

; #define PG8_STAGE(bufoff, gbase, voff) do { _Pragma("unroll") for (int _i = 0; _i < 2; ++_i) \
;         __builtin_amdgcn_global_load_lds((const unsigned*)((const char*)(gbase) + (voff)[_i]), (PG8_LAS unsigned*)(lds + (bufoff) + ldsw + _i * 8192), 16, 0, 0); } while (0)
; #define PG8_LDA(dst, b, h) do { _Pragma("unroll") for (int m = 0; m < 4; ++m) _Pragma("unroll") for (int k = 0; k < 2; ++k) dst[m][k] = *(const PG8_LAS bf16x8*)(lds + PG8_SA(b, h) + aoff + m * 2048 + k * 1024); } while (0)
; #define PG8_LDB(dst, b, h) do { _Pragma("unroll") for (int n = 0; n < 2; ++n) _Pragma("unroll") for (int k = 0; k < 2; ++k) dst[n][k] = *(const PG8_LAS bf16x8*)(lds + PG8_SB(b, h) + boff + n * 2048 + k * 1024); } while (0)
; #define PG8_WAIT_V(n) asm volatile("s_waitcnt vmcnt(" #n ")" ::: "memory")
; #define PG8_WAIT_L(n) asm volatile("s_waitcnt lgkmcnt(" #n ")" ::: "memory")
; #define PG8_BAR __builtin_amdgcn_s_barrier()
; #define PG8_SCHED __builtin_amdgcn_sched_barrier(0)
; template <class Epi, class Sched, bool ALIGN_EPI = false, bool SP2 = false>
; __device__ __forceinline__ void gemm_phase(PG8_LAS unsigned char* lds, const Gemm g, const Sched& S, const Epi& E) {
;     ...
;         const bool has_next = S.next(ui + 1, nxt);
;         const char* nA = has_next ? (const char*)g.A + (size_t)nxt.pm * tstep : cA; const char* nB = has_next ? (const char*)g.Bt + (size_t)nxt.pn * tstep : cB;
;         for (int t = 0; t < nt; t += 2) {
;             const bool last = (t == nt - 2);
;             const char* a1 = cA + (size_t)(t + 1) * kstep;
;             const char* a2 = last ? nA : cA + (size_t)(t + 2) * kstep; const char* b2 = last ? nB : cB + (size_t)(t + 2) * kstep;
;             const char* a3 = a2 + kstep; const char* b3 = b2 + kstep;
;             if (last && has_next) S.a_ready(nxt);
;             if constexpr (SP2) {
;             PG8_LDB(B0, 0, 0); PG8_LDB(B1, 0, 1); PG8_SCHED; PG8_LDA(At, 0, 0); PG8_STAGE(PG8_SA(1, 1), a1 + hstep, voffA);
;             PG8_WAIT_V(8); PG8_WAIT_L(0); PG8_BAR; PG8_MMA(0, 0, At, B0); PG8_MMA(0, 1, At, B1); PG8_BAR; PG8_SCHED;
;             PG8_LDA(At, 0, 1); PG8_STAGE(PG8_SB(0, 0), b2, voffB); PG8_STAGE(PG8_SB(0, 1), b2 + hstep, voffB); PG8_STAGE(PG8_SA(0, 0), a2, voffA);
;             PG8_WAIT_V(8); PG8_WAIT_L(0); PG8_BAR; PG8_MMA(1, 0, At, B0); PG8_MMA(1, 1, At, B1); PG8_BAR; PG8_SCHED;
.LBB0_302:
	s_ashr_i32 s21, s20, 31
	s_lshl_b64 s[22:23], s[20:21], 19
	s_add_u32 s22, s34, s22
	s_addc_u32 s23, s35, s23
	s_and_b64 s[24:25], s[6:7], exec
	s_cselect_b32 s17, s23, s27
	s_cselect_b32 s21, s22, s26
	s_ashr_i32 s19, s18, 31
	s_lshl_b64 s[24:25], s[18:19], 19
	s_add_u32 s24, s40, s24
	s_addc_u32 s25, s41, s25
	s_and_b64 s[30:31], s[6:7], exec
	s_cselect_b32 s19, s25, s29
	s_cselect_b32 s54, s24, s28
	s_add_u32 s26, s26, 0x40080
	s_addc_u32 s27, s27, 0
	s_add_u32 s64, s28, 0x100
	v_mov_b32_e32 v2, 0
	s_addc_u32 s71, s29, 0
	s_mov_b32 s73, -2
	s_add_u32 s28, s26, 0xfffc0080
	s_addc_u32 s29, s27, -1
	s_add_i32 s74, 0, 0x10000
	s_cmp_eq_u32 s73, 12
	s_cselect_b32 s31, s17, s29
	s_cselect_b32 s30, s21, s28
	v_add_u32_e32 v145, s74, v137
	s_cselect_b32 s29, s19, s71
	s_cselect_b32 s28, s54, s64
	s_add_i32 s76, 0, 0x14000
	ds_read_b128 v[152:155], v145
	ds_read_b128 v[156:159], v145 offset:1024
	ds_read_b128 v[160:163], v145 offset:2048
	ds_read_b128 v[164:167], v145 offset:3072
	v_add_u32_e32 v145, s76, v137
	ds_read_b128 v[168:171], v145
	ds_read_b128 v[172:175], v145 offset:1024
	ds_read_b128 v[176:179], v145 offset:2048
	ds_read_b128 v[180:183], v145 offset:3072
	v_lshl_add_u64 v[202:203], s[26:27], 0, v[148:149]
	s_add_i32 m0, s43, 0xc000
	ds_read_b128 v[208:211], v143
	ds_read_b128 v[212:215], v143 offset:1024
	ds_read_b128 v[216:219], v143 offset:2048
	ds_read_b128 v[220:223], v143 offset:3072
	ds_read_b128 v[224:227], v143 offset:4096
	ds_read_b128 v[228:231], v143 offset:5120
	ds_read_b128 v[232:235], v143 offset:6144
	ds_read_b128 v[236:239], v143 offset:7168
	global_load_lds_dwordx4 v[202:203], off
	v_lshl_add_u64 v[202:203], s[26:27], 0, v[150:151]
	s_add_i32 m0, s43, 0xe000
	s_nop 0
	global_load_lds_dwordx4 v[202:203], off
	s_waitcnt vmcnt(8)
	s_waitcnt lgkmcnt(0)
	s_barrier
	s_setprio 1
	s_waitcnt lgkmcnt(0)
	v_mfma_f32_16x16x32_bf16 v[126:129], v[152:155], v[208:211], 0
	v_mfma_f32_16x16x32_bf16 v[122:125], v[160:163], v[208:211], 0
	v_mfma_f32_16x16x32_bf16 v[114:117], v[152:155], v[216:219], 0
	v_mfma_f32_16x16x32_bf16 v[106:109], v[160:163], v[216:219], 0
	v_mfma_f32_16x16x32_bf16 v[98:101], v[152:155], v[224:227], 0
	v_mfma_f32_16x16x32_bf16 v[90:93], v[160:163], v[224:227], 0
	v_mfma_f32_16x16x32_bf16 v[82:85], v[152:155], v[232:235], 0
	v_mfma_f32_16x16x32_bf16 v[74:77], v[160:163], v[232:235], 0
	v_mfma_f32_16x16x32_bf16 v[126:129], v[156:159], v[212:215], v[126:129]
	v_mfma_f32_16x16x32_bf16 v[122:125], v[164:167], v[212:215], v[122:125]
	v_mfma_f32_16x16x32_bf16 v[114:117], v[156:159], v[220:223], v[114:117]
	v_mfma_f32_16x16x32_bf16 v[106:109], v[164:167], v[220:223], v[106:109]
	v_mfma_f32_16x16x32_bf16 v[98:101], v[156:159], v[228:231], v[98:101]
	v_mfma_f32_16x16x32_bf16 v[90:93], v[164:167], v[228:231], v[90:93]
	v_mfma_f32_16x16x32_bf16 v[82:85], v[156:159], v[236:239], v[82:85]
	v_mfma_f32_16x16x32_bf16 v[74:77], v[164:167], v[236:239], v[74:77]
	s_setprio 0
	s_setprio 1
	v_mfma_f32_16x16x32_bf16 v[118:121], v[168:171], v[208:211], 0
	v_mfma_f32_16x16x32_bf16 v[110:113], v[176:179], v[208:211], 0
	v_mfma_f32_16x16x32_bf16 v[102:105], v[168:171], v[216:219], 0
	v_mfma_f32_16x16x32_bf16 v[94:97], v[176:179], v[216:219], 0
	v_mfma_f32_16x16x32_bf16 v[86:89], v[168:171], v[224:227], 0
	v_mfma_f32_16x16x32_bf16 v[78:81], v[176:179], v[224:227], 0
	v_mfma_f32_16x16x32_bf16 v[70:73], v[168:171], v[232:235], 0
	v_mfma_f32_16x16x32_bf16 v[66:69], v[176:179], v[232:235], 0
	v_mfma_f32_16x16x32_bf16 v[118:121], v[172:175], v[212:215], v[118:121]
	v_mfma_f32_16x16x32_bf16 v[110:113], v[180:183], v[212:215], v[110:113]
	v_mfma_f32_16x16x32_bf16 v[102:105], v[172:175], v[220:223], v[102:105]
	v_mfma_f32_16x16x32_bf16 v[94:97], v[180:183], v[220:223], v[94:97]
	v_mfma_f32_16x16x32_bf16 v[86:89], v[172:175], v[228:231], v[86:89]
	v_mfma_f32_16x16x32_bf16 v[78:81], v[180:183], v[228:231], v[78:81]
	v_mfma_f32_16x16x32_bf16 v[70:73], v[172:175], v[236:239], v[70:73]
	v_mfma_f32_16x16x32_bf16 v[66:69], v[180:183], v[236:239], v[66:69]
	s_setprio 0
	s_barrier
	s_add_i32 s74, s74, s42
	v_lshl_add_u64 v[202:203], s[28:29], 0, v[132:133]
	s_mov_b32 m0, s74
	ds_read_b128 v[208:211], v143 offset:16384
	ds_read_b128 v[212:215], v143 offset:17408
	ds_read_b128 v[216:219], v143 offset:18432
	ds_read_b128 v[220:223], v143 offset:19456
	ds_read_b128 v[224:227], v143 offset:20480
	ds_read_b128 v[228:231], v143 offset:21504
	ds_read_b128 v[232:235], v143 offset:22528
	ds_read_b128 v[236:239], v143 offset:23552
	global_load_lds_dwordx4 v[202:203], off
	s_add_i32 m0, s74, 0x2000
	s_add_u32 s74, s28, 0x40000
	v_lshl_add_u64 v[204:205], s[28:29], 0, v[130:131]
	s_addc_u32 s75, s29, 0
	s_add_i32 s76, s76, s42
	global_load_lds_dwordx4 v[204:205], off
	v_lshl_add_u64 v[240:241], s[74:75], 0, v[132:133]
	s_mov_b32 m0, s76
	v_lshl_add_u64 v[242:243], s[30:31], 0, v[130:131]
	global_load_lds_dwordx4 v[240:241], off
	v_lshl_add_u64 v[240:241], s[74:75], 0, v[130:131]
	s_add_i32 m0, s76, 0x2000
	s_nop 0
	global_load_lds_dwordx4 v[240:241], off
	v_lshl_add_u64 v[240:241], s[30:31], 0, v[132:133]
	s_mov_b32 m0, s43
	s_nop 0
	global_load_lds_dwordx4 v[240:241], off
	s_mov_b32 m0, s44
	s_nop 0
	global_load_lds_dwordx4 v[242:243], off
	s_waitcnt vmcnt(8)
	s_waitcnt lgkmcnt(0)
	s_barrier
; #define PG8_STAGE(bufoff, gbase, voff) do { _Pragma("unroll") for (int _i = 0; _i < 2; ++_i) \
;         __builtin_amdgcn_global_load_lds((const unsigned*)((const char*)(gbase) + (voff)[_i]), (PG8_LAS unsigned*)(lds + (bufoff) + ldsw + _i * 8192), 16, 0, 0); } while (0)
; #define PG8_LDA(dst, b, h) do { _Pragma("unroll") for (int m = 0; m < 4; ++m) _Pragma("unroll") for (int k = 0; k < 2; ++k) dst[m][k] = *(const PG8_LAS bf16x8*)(lds + PG8_SA(b, h) + aoff + m * 2048 + k * 1024); } while (0)
; #define PG8_LDB(dst, b, h) do { _Pragma("unroll") for (int n = 0; n < 2; ++n) _Pragma("unroll") for (int k = 0; k < 2; ++k) dst[n][k] = *(const PG8_LAS bf16x8*)(lds + PG8_SB(b, h) + boff + n * 2048 + k * 1024); } while (0)
; #define PG8_MMA(ai, bj, At, Bt) do { __builtin_amdgcn_s_setprio(1); _Pragma("unroll") for (int m = 0; m < 4; ++m) _Pragma("unroll") for (int n = 0; n < 2; ++n) _Pragma("unroll") for (int k = 0; k < 2; ++k) \
;         acc[ai][bj][m][n] = __builtin_amdgcn_mfma_f32_16x16x32_bf16(Bt[n][k], At[m][k], acc[ai][bj][m][n], 0, 0, 0); __builtin_amdgcn_s_setprio(0); } while (0)
; #define PG8_WAIT_V(n) asm volatile("s_waitcnt vmcnt(" #n ")" ::: "memory")
; #define PG8_WAIT_L(n) asm volatile("s_waitcnt lgkmcnt(" #n ")" ::: "memory")
; #define PG8_BAR __builtin_amdgcn_s_barrier()
; #define PG8_SCHED __builtin_amdgcn_sched_barrier(0)
; template <class Epi, class Sched, bool ALIGN_EPI = false, bool SP2 = false>
; __device__ __forceinline__ void gemm_phase(PG8_LAS unsigned char* lds, const Gemm g, const Sched& S, const Epi& E) {
;     ...
;             PG8_WAIT_V(8); PG8_WAIT_L(0); PG8_BAR; PG8_MMA(0, 0, At, B0); PG8_MMA(0, 1, At, B1); PG8_BAR; PG8_SCHED;
;             PG8_LDA(At, 0, 1); PG8_STAGE(PG8_SB(0, 0), b2, voffB); PG8_STAGE(PG8_SB(0, 1), b2 + hstep, voffB); PG8_STAGE(PG8_SA(0, 0), a2, voffA);
;             PG8_WAIT_V(8); PG8_WAIT_L(0); PG8_BAR; PG8_MMA(1, 0, At, B0); PG8_MMA(1, 1, At, B1); PG8_BAR; PG8_SCHED;
;             PG8_LDB(B0, 1, 0); PG8_LDB(B1, 1, 1); PG8_SCHED; PG8_LDA(At, 1, 0); PG8_STAGE(PG8_SA(0, 1), a2 + hstep, voffA);
;             PG8_WAIT_V(8); PG8_WAIT_L(0); PG8_BAR; PG8_MMA(0, 0, At, B0); PG8_MMA(0, 1, At, B1); PG8_BAR; PG8_SCHED;
	s_setprio 1
	s_waitcnt lgkmcnt(0)
	v_mfma_f32_16x16x32_bf16 v[62:65], v[152:155], v[208:211], 0
	v_mfma_f32_16x16x32_bf16 v[58:61], v[160:163], v[208:211], 0
	v_mfma_f32_16x16x32_bf16 v[50:53], v[152:155], v[216:219], 0
	v_mfma_f32_16x16x32_bf16 v[42:45], v[160:163], v[216:219], 0
	v_mfma_f32_16x16x32_bf16 v[34:37], v[152:155], v[224:227], 0
	v_mfma_f32_16x16x32_bf16 v[26:29], v[160:163], v[224:227], 0
	v_mfma_f32_16x16x32_bf16 v[18:21], v[152:155], v[232:235], 0
	v_mfma_f32_16x16x32_bf16 v[10:13], v[160:163], v[232:235], 0
	v_mfma_f32_16x16x32_bf16 v[62:65], v[156:159], v[212:215], v[62:65]
	v_mfma_f32_16x16x32_bf16 v[58:61], v[164:167], v[212:215], v[58:61]
	v_mfma_f32_16x16x32_bf16 v[50:53], v[156:159], v[220:223], v[50:53]
	v_mfma_f32_16x16x32_bf16 v[42:45], v[164:167], v[220:223], v[42:45]
	v_mfma_f32_16x16x32_bf16 v[34:37], v[156:159], v[228:231], v[34:37]
	v_mfma_f32_16x16x32_bf16 v[26:29], v[164:167], v[228:231], v[26:29]
	v_mfma_f32_16x16x32_bf16 v[18:21], v[156:159], v[236:239], v[18:21]
	v_mfma_f32_16x16x32_bf16 v[10:13], v[164:167], v[236:239], v[10:13]
	s_setprio 0
	s_setprio 1
	v_mfma_f32_16x16x32_bf16 v[54:57], v[168:171], v[208:211], 0
	v_mfma_f32_16x16x32_bf16 v[46:49], v[176:179], v[208:211], 0
	v_mfma_f32_16x16x32_bf16 v[38:41], v[168:171], v[216:219], 0
	v_mfma_f32_16x16x32_bf16 v[30:33], v[176:179], v[216:219], 0
	v_mfma_f32_16x16x32_bf16 v[22:25], v[168:171], v[224:227], 0
	v_mfma_f32_16x16x32_bf16 v[14:17], v[176:179], v[224:227], 0
	v_mfma_f32_16x16x32_bf16 v[6:9], v[168:171], v[232:235], 0
	v_mfma_f32_16x16x32_bf16 v[2:5], v[176:179], v[232:235], 0
	v_mfma_f32_16x16x32_bf16 v[54:57], v[172:175], v[212:215], v[54:57]
	v_mfma_f32_16x16x32_bf16 v[46:49], v[180:183], v[212:215], v[46:49]
	v_mfma_f32_16x16x32_bf16 v[38:41], v[172:175], v[220:223], v[38:41]
	v_mfma_f32_16x16x32_bf16 v[30:33], v[180:183], v[220:223], v[30:33]
	v_mfma_f32_16x16x32_bf16 v[22:25], v[172:175], v[228:231], v[22:25]
	v_mfma_f32_16x16x32_bf16 v[14:17], v[180:183], v[228:231], v[14:17]
	v_mfma_f32_16x16x32_bf16 v[6:9], v[172:175], v[236:239], v[6:9]
	v_mfma_f32_16x16x32_bf16 v[2:5], v[180:183], v[236:239], v[2:5]
	s_setprio 0
	s_barrier
	s_add_i32 s74, 0, 0x18000
	v_add_u32_e32 v145, s74, v137
	s_add_i32 s75, 0, 0x1c000
	ds_read_b128 v[152:155], v145
	ds_read_b128 v[156:159], v145 offset:1024
	ds_read_b128 v[160:163], v145 offset:2048
	ds_read_b128 v[164:167], v145 offset:3072
	v_add_u32_e32 v145, s75, v137
	ds_read_b128 v[168:171], v145
	ds_read_b128 v[172:175], v145 offset:1024
	ds_read_b128 v[176:179], v145 offset:2048
	ds_read_b128 v[180:183], v145 offset:3072
	s_add_u32 s30, s30, 0x40000
	s_addc_u32 s31, s31, 0
	s_mov_b32 m0, s45
	v_lshl_add_u64 v[244:245], s[30:31], 0, v[132:133]
	ds_read_b128 v[208:211], v143 offset:32768
	ds_read_b128 v[212:215], v143 offset:33792
	ds_read_b128 v[216:219], v143 offset:34816
	ds_read_b128 v[220:223], v143 offset:35840
	ds_read_b128 v[224:227], v143 offset:36864
	ds_read_b128 v[228:231], v143 offset:37888
	ds_read_b128 v[232:235], v143 offset:38912
	ds_read_b128 v[236:239], v143 offset:39936
	global_load_lds_dwordx4 v[244:245], off
	v_lshl_add_u64 v[244:245], s[30:31], 0, v[130:131]
	s_mov_b32 m0, s46
	s_nop 0
	global_load_lds_dwordx4 v[244:245], off
	s_waitcnt vmcnt(8)
	s_waitcnt lgkmcnt(0)
	s_barrier
	s_setprio 1
	s_waitcnt lgkmcnt(0)
	v_mfma_f32_16x16x32_bf16 v[126:129], v[152:155], v[208:211], v[126:129]
	v_mfma_f32_16x16x32_bf16 v[122:125], v[160:163], v[208:211], v[122:125]
	v_mfma_f32_16x16x32_bf16 v[114:117], v[152:155], v[216:219], v[114:117]
	v_mfma_f32_16x16x32_bf16 v[106:109], v[160:163], v[216:219], v[106:109]
	v_mfma_f32_16x16x32_bf16 v[98:101], v[152:155], v[224:227], v[98:101]
	v_mfma_f32_16x16x32_bf16 v[90:93], v[160:163], v[224:227], v[90:93]
	v_mfma_f32_16x16x32_bf16 v[82:85], v[152:155], v[232:235], v[82:85]
	v_mfma_f32_16x16x32_bf16 v[74:77], v[160:163], v[232:235], v[74:77]
	v_mfma_f32_16x16x32_bf16 v[126:129], v[156:159], v[212:215], v[126:129]
	v_mfma_f32_16x16x32_bf16 v[122:125], v[164:167], v[212:215], v[122:125]
	v_mfma_f32_16x16x32_bf16 v[114:117], v[156:159], v[220:223], v[114:117]
	v_mfma_f32_16x16x32_bf16 v[106:109], v[164:167], v[220:223], v[106:109]
	v_mfma_f32_16x16x32_bf16 v[98:101], v[156:159], v[228:231], v[98:101]
	v_mfma_f32_16x16x32_bf16 v[90:93], v[164:167], v[228:231], v[90:93]
	v_mfma_f32_16x16x32_bf16 v[82:85], v[156:159], v[236:239], v[82:85]
	v_mfma_f32_16x16x32_bf16 v[74:77], v[164:167], v[236:239], v[74:77]
	s_setprio 0
	s_setprio 1
	v_mfma_f32_16x16x32_bf16 v[118:121], v[168:171], v[208:211], v[118:121]
	v_mfma_f32_16x16x32_bf16 v[110:113], v[176:179], v[208:211], v[110:113]
	v_mfma_f32_16x16x32_bf16 v[102:105], v[168:171], v[216:219], v[102:105]
	v_mfma_f32_16x16x32_bf16 v[94:97], v[176:179], v[216:219], v[94:97]
	v_mfma_f32_16x16x32_bf16 v[86:89], v[168:171], v[224:227], v[86:89]
	v_mfma_f32_16x16x32_bf16 v[78:81], v[176:179], v[224:227], v[78:81]
	v_mfma_f32_16x16x32_bf16 v[70:73], v[168:171], v[232:235], v[70:73]
	v_mfma_f32_16x16x32_bf16 v[66:69], v[176:179], v[232:235], v[66:69]
	v_mfma_f32_16x16x32_bf16 v[118:121], v[172:175], v[212:215], v[118:121]
	v_mfma_f32_16x16x32_bf16 v[110:113], v[180:183], v[212:215], v[110:113]
	v_mfma_f32_16x16x32_bf16 v[102:105], v[172:175], v[220:223], v[102:105]
	v_mfma_f32_16x16x32_bf16 v[94:97], v[180:183], v[220:223], v[94:97]
	v_mfma_f32_16x16x32_bf16 v[86:89], v[172:175], v[228:231], v[86:89]
	v_mfma_f32_16x16x32_bf16 v[78:81], v[180:183], v[228:231], v[78:81]
	v_mfma_f32_16x16x32_bf16 v[70:73], v[172:175], v[236:239], v[70:73]
	v_mfma_f32_16x16x32_bf16 v[66:69], v[180:183], v[236:239], v[66:69]
	s_setprio 0
	s_barrier
; #define PG8_STAGE(bufoff, gbase, voff) do { _Pragma("unroll") for (int _i = 0; _i < 2; ++_i) \
;         __builtin_amdgcn_global_load_lds((const unsigned*)((const char*)(gbase) + (voff)[_i]), (PG8_LAS unsigned*)(lds + (bufoff) + ldsw + _i * 8192), 16, 0, 0); } while (0)
; #define PG8_LDA(dst, b, h) do { _Pragma("unroll") for (int m = 0; m < 4; ++m) _Pragma("unroll") for (int k = 0; k < 2; ++k) dst[m][k] = *(const PG8_LAS bf16x8*)(lds + PG8_SA(b, h) + aoff + m * 2048 + k * 1024); } while (0)
; #define PG8_LDB(dst, b, h) do { _Pragma("unroll") for (int n = 0; n < 2; ++n) _Pragma("unroll") for (int k = 0; k < 2; ++k) dst[n][k] = *(const PG8_LAS bf16x8*)(lds + PG8_SB(b, h) + boff + n * 2048 + k * 1024); } while (0)
; template <class Epi, class Sched, bool ALIGN_EPI = false, bool SP2 = false>
; __device__ __forceinline__ void gemm_phase(PG8_LAS unsigned char* lds, const Gemm g, const Sched& S, const Epi& E) {
;     ...
;         for (int t = 0; t < nt; t += 2) {
;             const bool last = (t == nt - 2);
;             const char* a1 = cA + (size_t)(t + 1) * kstep;
;             const char* a2 = last ? nA : cA + (size_t)(t + 2) * kstep; const char* b2 = last ? nB : cB + (size_t)(t + 2) * kstep;
;             const char* a3 = a2 + kstep; const char* b3 = b2 + kstep;
;             if (last && has_next) S.a_ready(nxt);
;             if constexpr (SP2) {
;             PG8_LDB(B0, 0, 0); PG8_LDB(B1, 0, 1); PG8_SCHED; PG8_LDA(At, 0, 0); PG8_STAGE(PG8_SA(1, 1), a1 + hstep, voffA);
;             PG8_WAIT_V(8); PG8_WAIT_L(0); PG8_BAR; PG8_MMA(0, 0, At, B0); PG8_MMA(0, 1, At, B1); PG8_BAR; PG8_SCHED;
;             PG8_LDA(At, 0, 1); PG8_STAGE(PG8_SB(0, 0), b2, voffB); PG8_STAGE(PG8_SB(0, 1), b2 + hstep, voffB); PG8_STAGE(PG8_SA(0, 0), a2, voffA);
;             PG8_WAIT_V(8); PG8_WAIT_L(0); PG8_BAR; PG8_MMA(1, 0, At, B0); PG8_MMA(1, 1, At, B1); PG8_BAR; PG8_SCHED;
;             PG8_LDB(B0, 1, 0); PG8_LDB(B1, 1, 1); PG8_SCHED; PG8_LDA(At, 1, 0); PG8_STAGE(PG8_SA(0, 1), a2 + hstep, voffA);
;             PG8_WAIT_V(8); PG8_WAIT_L(0); PG8_BAR; PG8_MMA(0, 0, At, B0); PG8_MMA(0, 1, At, B1); PG8_BAR; PG8_SCHED;
;             PG8_LDA(At, 1, 1); PG8_STAGE(PG8_SB(1, 0), b3, voffB); PG8_STAGE(PG8_SB(1, 1), b3 + hstep, voffB); PG8_STAGE(PG8_SA(1, 0), a3, voffA);
;             PG8_WAIT_V(8); PG8_WAIT_L(0); PG8_BAR; PG8_MMA(1, 0, At, B0); PG8_MMA(1, 1, At, B1); PG8_BAR; PG8_SCHED;
	s_add_i32 s30, s74, s42
	v_lshl_add_u64 v[202:203], v[202:203], 0, s[66:67]
	s_mov_b32 m0, s30
	ds_read_b128 v[208:211], v143 offset:49152
	ds_read_b128 v[212:215], v143 offset:50176
	ds_read_b128 v[216:219], v143 offset:51200
	ds_read_b128 v[220:223], v143 offset:52224
	ds_read_b128 v[224:227], v143 offset:53248
	ds_read_b128 v[228:231], v143 offset:54272
	ds_read_b128 v[232:235], v143 offset:55296
	ds_read_b128 v[236:239], v143 offset:56320
	global_load_lds_dwordx4 v[202:203], off
	s_add_i32 m0, s30, 0x2000
	s_add_u32 s28, s28, 0x40080
	v_lshl_add_u64 v[202:203], v[204:205], 0, s[66:67]
	s_addc_u32 s29, s29, 0
	s_add_i32 s30, s75, s42
	global_load_lds_dwordx4 v[202:203], off
	v_lshl_add_u64 v[202:203], s[28:29], 0, v[132:133]
	s_mov_b32 m0, s30
	s_nop 0
	global_load_lds_dwordx4 v[202:203], off
	v_lshl_add_u64 v[202:203], s[28:29], 0, v[130:131]
	s_add_i32 m0, s30, 0x2000
	s_nop 0
	global_load_lds_dwordx4 v[202:203], off
	v_lshl_add_u64 v[202:203], v[240:241], 0, s[66:67]
	s_mov_b32 m0, s49
	s_nop 0
	global_load_lds_dwordx4 v[202:203], off
	v_lshl_add_u64 v[202:203], v[242:243], 0, s[66:67]
	s_mov_b32 m0, s50
	s_nop 0
	global_load_lds_dwordx4 v[202:203], off
	s_waitcnt vmcnt(8)
	s_waitcnt lgkmcnt(0)
	s_barrier
	s_setprio 1
	s_waitcnt lgkmcnt(0)
	v_mfma_f32_16x16x32_bf16 v[62:65], v[152:155], v[208:211], v[62:65]
	v_mfma_f32_16x16x32_bf16 v[58:61], v[160:163], v[208:211], v[58:61]
	v_mfma_f32_16x16x32_bf16 v[50:53], v[152:155], v[216:219], v[50:53]
	v_mfma_f32_16x16x32_bf16 v[42:45], v[160:163], v[216:219], v[42:45]
	v_mfma_f32_16x16x32_bf16 v[34:37], v[152:155], v[224:227], v[34:37]
	v_mfma_f32_16x16x32_bf16 v[26:29], v[160:163], v[224:227], v[26:29]
	v_mfma_f32_16x16x32_bf16 v[18:21], v[152:155], v[232:235], v[18:21]
	v_mfma_f32_16x16x32_bf16 v[10:13], v[160:163], v[232:235], v[10:13]
	v_mfma_f32_16x16x32_bf16 v[62:65], v[156:159], v[212:215], v[62:65]
	v_mfma_f32_16x16x32_bf16 v[58:61], v[164:167], v[212:215], v[58:61]
	v_mfma_f32_16x16x32_bf16 v[50:53], v[156:159], v[220:223], v[50:53]
	v_mfma_f32_16x16x32_bf16 v[42:45], v[164:167], v[220:223], v[42:45]
	v_mfma_f32_16x16x32_bf16 v[34:37], v[156:159], v[228:231], v[34:37]
	v_mfma_f32_16x16x32_bf16 v[26:29], v[164:167], v[228:231], v[26:29]
	v_mfma_f32_16x16x32_bf16 v[18:21], v[156:159], v[236:239], v[18:21]
	v_mfma_f32_16x16x32_bf16 v[10:13], v[164:167], v[236:239], v[10:13]
	s_setprio 0
	s_setprio 1
	v_mfma_f32_16x16x32_bf16 v[54:57], v[168:171], v[208:211], v[54:57]
	v_mfma_f32_16x16x32_bf16 v[46:49], v[176:179], v[208:211], v[46:49]
	v_mfma_f32_16x16x32_bf16 v[38:41], v[168:171], v[216:219], v[38:41]
	v_mfma_f32_16x16x32_bf16 v[30:33], v[176:179], v[216:219], v[30:33]
	v_mfma_f32_16x16x32_bf16 v[22:25], v[168:171], v[224:227], v[22:25]
	v_mfma_f32_16x16x32_bf16 v[14:17], v[176:179], v[224:227], v[14:17]
	v_mfma_f32_16x16x32_bf16 v[6:9], v[168:171], v[232:235], v[6:9]
	v_mfma_f32_16x16x32_bf16 v[2:5], v[176:179], v[232:235], v[2:5]
	v_mfma_f32_16x16x32_bf16 v[54:57], v[172:175], v[212:215], v[54:57]
	v_mfma_f32_16x16x32_bf16 v[46:49], v[180:183], v[212:215], v[46:49]
	v_mfma_f32_16x16x32_bf16 v[38:41], v[172:175], v[220:223], v[38:41]
	v_mfma_f32_16x16x32_bf16 v[30:33], v[180:183], v[220:223], v[30:33]
	v_mfma_f32_16x16x32_bf16 v[22:25], v[172:175], v[228:231], v[22:25]
	v_mfma_f32_16x16x32_bf16 v[14:17], v[180:183], v[228:231], v[14:17]
	v_mfma_f32_16x16x32_bf16 v[6:9], v[172:175], v[236:239], v[6:9]
	v_mfma_f32_16x16x32_bf16 v[2:5], v[180:183], v[236:239], v[2:5]
	s_setprio 0
	s_barrier
	s_add_i32 s73, s73, 2
	s_add_u32 s26, s26, 0x100
	s_addc_u32 s27, s27, 0
	s_add_u32 s64, s64, 0x100
	s_addc_u32 s71, s71, 0
	s_cmp_gt_u32 s73, 13
	s_cbranch_scc0 .LBB0_303
	s_branch .Lpeel_e_exit
	s_nop 0

; #define PG8_BAR __builtin_amdgcn_s_barrier()
; template <class Epi, class Sched, bool ALIGN_EPI = false, bool SP2 = false>
; __device__ __forceinline__ void gemm_phase(PG8_LAS unsigned char* lds, const Gemm g, const Sched& S, const Epi& E) {
;     ...
;         if constexpr (ALIGN_EPI) { if (wr == 0) PG8_BAR; }
;         if constexpr (!Epi::AFTER_DRAIN) { E(acc, cur, wr, wc, fr, fq); S.done(cur); }
;         if (!has_next) break;
.Lpeel_e_exit:
	s_and_b64 vcc, exec, s[12:13]
	s_cbranch_vccz .LBB0_306
	s_barrier

; #define PG8_STAGE(bufoff, gbase, voff) do { _Pragma("unroll") for (int _i = 0; _i < 2; ++_i) \
;         __builtin_amdgcn_global_load_lds((const unsigned*)((const char*)(gbase) + (voff)[_i]), (PG8_LAS unsigned*)(lds + (bufoff) + ldsw + _i * 8192), 16, 0, 0); } while (0)
; #define PG8_LDA(dst, b, h) do { _Pragma("unroll") for (int m = 0; m < 4; ++m) _Pragma("unroll") for (int k = 0; k < 2; ++k) dst[m][k] = *(const PG8_LAS bf16x8*)(lds + PG8_SA(b, h) + aoff + m * 2048 + k * 1024); } while (0)
; #define PG8_LDB(dst, b, h) do { _Pragma("unroll") for (int n = 0; n < 2; ++n) _Pragma("unroll") for (int k = 0; k < 2; ++k) dst[n][k] = *(const PG8_LAS bf16x8*)(lds + PG8_SB(b, h) + boff + n * 2048 + k * 1024); } while (0)
; #define PG8_MMA(ai, bj, At, Bt) do { __builtin_amdgcn_s_setprio(1); _Pragma("unroll") for (int m = 0; m < 4; ++m) _Pragma("unroll") for (int n = 0; n < 2; ++n) _Pragma("unroll") for (int k = 0; k < 2; ++k) \
;         acc[ai][bj][m][n] = __builtin_amdgcn_mfma_f32_16x16x32_bf16(Bt[n][k], At[m][k], acc[ai][bj][m][n], 0, 0, 0); __builtin_amdgcn_s_setprio(0); } while (0)
; #define PG8_WAIT_V(n) asm volatile("s_waitcnt vmcnt(" #n ")" ::: "memory")
; #define PG8_WAIT_L(n) asm volatile("s_waitcnt lgkmcnt(" #n ")" ::: "memory")
; #define PG8_BAR __builtin_amdgcn_s_barrier()
; #define PG8_SCHED __builtin_amdgcn_sched_barrier(0)
; template <class Epi, class Sched, bool ALIGN_EPI = false, bool SP2 = false>
; __device__ __forceinline__ void gemm_phase(PG8_LAS unsigned char* lds, const Gemm g, const Sched& S, const Epi& E) {
;     ...
;             PG8_LDB(B0, 0, 0); PG8_LDB(B1, 0, 1); PG8_SCHED; PG8_LDA(At, 0, 0); PG8_STAGE(PG8_SA(1, 1), a1 + hstep, voffA);
;             PG8_WAIT_V(8); PG8_WAIT_L(0); PG8_BAR; PG8_MMA(0, 0, At, B0); PG8_MMA(0, 1, At, B1); PG8_BAR; PG8_SCHED;
;     ...
;         for (int a = 0; a < 2; ++a)
; #pragma unroll
;             for (int b = 0; b < 2; ++b)
; #pragma unroll
;                 for (int m = 0; m < 4; ++m)
; #pragma unroll
;                     for (int n = 0; n < 2; ++n) acc[a][b][m][n] = (f32x4){0.f, 0.f, 0.f, 0.f};
.LBB0_848:
	s_add_u32 s48, s48, 0x80
	s_addc_u32 s49, s49, 0
	s_add_u32 s80, s76, 0x100
	v_mov_b32_e32 v2, 0
	s_addc_u32 s81, s77, 0
	s_mov_b32 s76, 0
	s_and_b32 s98, s101, 7
	s_cmp_lg_u32 s98, 0
	s_cbranch_scc0 .Lpeel_r
	v_mov_b32_e32 v3, v2
	v_mov_b32_e32 v4, v2
	v_mov_b32_e32 v5, v2
	v_mov_b32_e32 v6, v2
	v_mov_b32_e32 v7, v2
	v_mov_b32_e32 v8, v2
	v_mov_b32_e32 v9, v2
	v_mov_b32_e32 v18, v2
	v_mov_b32_e32 v19, v2
	v_mov_b32_e32 v20, v2
	v_mov_b32_e32 v21, v2
	v_mov_b32_e32 v22, v2
	v_mov_b32_e32 v23, v2
	v_mov_b32_e32 v24, v2
	v_mov_b32_e32 v25, v2
	v_mov_b32_e32 v34, v2
	v_mov_b32_e32 v35, v2
	v_mov_b32_e32 v36, v2
	v_mov_b32_e32 v37, v2
	v_mov_b32_e32 v38, v2
	v_mov_b32_e32 v39, v2
	v_mov_b32_e32 v40, v2
	v_mov_b32_e32 v41, v2
	v_mov_b32_e32 v50, v2
	v_mov_b32_e32 v51, v2
	v_mov_b32_e32 v52, v2
	v_mov_b32_e32 v53, v2
	v_mov_b32_e32 v54, v2
	v_mov_b32_e32 v55, v2
	v_mov_b32_e32 v56, v2
	v_mov_b32_e32 v57, v2
	v_mov_b32_e32 v10, v2
	v_mov_b32_e32 v11, v2
	v_mov_b32_e32 v12, v2
	v_mov_b32_e32 v13, v2
	v_mov_b32_e32 v14, v2
	v_mov_b32_e32 v15, v2
	v_mov_b32_e32 v16, v2
	v_mov_b32_e32 v17, v2
	v_mov_b32_e32 v26, v2
	v_mov_b32_e32 v27, v2
	v_mov_b32_e32 v28, v2
	v_mov_b32_e32 v29, v2
	v_mov_b32_e32 v30, v2
	v_mov_b32_e32 v31, v2
	v_mov_b32_e32 v32, v2
	v_mov_b32_e32 v33, v2
	v_mov_b32_e32 v42, v2
	v_mov_b32_e32 v43, v2
	v_mov_b32_e32 v44, v2
	v_mov_b32_e32 v45, v2
	v_mov_b32_e32 v46, v2
	v_mov_b32_e32 v47, v2
	v_mov_b32_e32 v48, v2
	v_mov_b32_e32 v49, v2
	v_mov_b32_e32 v58, v2
	v_mov_b32_e32 v59, v2
	v_mov_b32_e32 v60, v2
	v_mov_b32_e32 v61, v2
	v_mov_b32_e32 v62, v2
	v_mov_b32_e32 v63, v2
	v_mov_b32_e32 v64, v2
	v_mov_b32_e32 v65, v2
	v_mov_b32_e32 v66, v2
	v_mov_b32_e32 v67, v2
	v_mov_b32_e32 v68, v2
	v_mov_b32_e32 v69, v2
	v_mov_b32_e32 v70, v2
	v_mov_b32_e32 v71, v2
	v_mov_b32_e32 v72, v2
	v_mov_b32_e32 v73, v2
	v_mov_b32_e32 v82, v2
	v_mov_b32_e32 v83, v2
	v_mov_b32_e32 v84, v2
	v_mov_b32_e32 v85, v2
	v_mov_b32_e32 v86, v2
	v_mov_b32_e32 v87, v2
	v_mov_b32_e32 v88, v2
	v_mov_b32_e32 v89, v2
	v_mov_b32_e32 v98, v2
	v_mov_b32_e32 v99, v2
	v_mov_b32_e32 v100, v2
	v_mov_b32_e32 v101, v2
	v_mov_b32_e32 v102, v2
	v_mov_b32_e32 v103, v2
	v_mov_b32_e32 v104, v2
	v_mov_b32_e32 v105, v2
	v_mov_b32_e32 v114, v2
	v_mov_b32_e32 v115, v2
	v_mov_b32_e32 v116, v2
	v_mov_b32_e32 v117, v2
	v_mov_b32_e32 v118, v2
	v_mov_b32_e32 v119, v2
	v_mov_b32_e32 v120, v2
	v_mov_b32_e32 v121, v2
	v_mov_b32_e32 v74, v2
	v_mov_b32_e32 v75, v2
	v_mov_b32_e32 v76, v2
	v_mov_b32_e32 v77, v2
	v_mov_b32_e32 v78, v2
	v_mov_b32_e32 v79, v2
	v_mov_b32_e32 v80, v2
	v_mov_b32_e32 v81, v2
	v_mov_b32_e32 v90, v2
	v_mov_b32_e32 v91, v2
	v_mov_b32_e32 v92, v2
	v_mov_b32_e32 v93, v2
	v_mov_b32_e32 v94, v2
	v_mov_b32_e32 v95, v2
	v_mov_b32_e32 v96, v2
	v_mov_b32_e32 v97, v2
	v_mov_b32_e32 v106, v2
	v_mov_b32_e32 v107, v2
	v_mov_b32_e32 v108, v2
	v_mov_b32_e32 v109, v2
	v_mov_b32_e32 v110, v2
	v_mov_b32_e32 v111, v2
	v_mov_b32_e32 v112, v2
	v_mov_b32_e32 v113, v2
	v_mov_b32_e32 v122, v2
	v_mov_b32_e32 v123, v2
	v_mov_b32_e32 v124, v2
	v_mov_b32_e32 v125, v2
	v_mov_b32_e32 v126, v2
	v_mov_b32_e32 v127, v2
	v_mov_b32_e32 v128, v2
	v_mov_b32_e32 v129, v2
	s_and_b32 s98, s101, 7
	s_cmp_eq_u32 s98, 1
	s_cbranch_scc1 .Lkq_1
	s_and_b32 s98, s101, 7
	s_cmp_eq_u32 s98, 2
	s_cbranch_scc1 .Lkq_2
	s_and_b32 s98, s101, 7
	s_cmp_eq_u32 s98, 3
	s_cbranch_scc1 .Lkq_3
	s_branch .Lkq_4
.Lpeel_r:
	s_add_i32 s82, s76, 2
	s_add_u32 s83, s48, 0x80
	s_addc_u32 s77, s49, 0
	s_add_i32 s59, 0, 0x10000
	s_cmp_eq_u32 s72, s76
	s_cselect_b32 s77, s9, s77
	s_cselect_b32 s76, s8, s83
	v_add_u32_e32 v136, s59, v147
	s_cselect_b32 vcc_hi, s47, s81
	s_cselect_b32 vcc_lo, s46, s80
	s_add_i32 s83, 0, 0x14000
	ds_read_b128 v[148:151], v136
	ds_read_b128 v[152:155], v136 offset:1024
	ds_read_b128 v[156:159], v136 offset:2048
	ds_read_b128 v[160:163], v136 offset:3072
	v_add_u32_e32 v136, s83, v147
	ds_read_b128 v[166:169], v136
	ds_read_b128 v[170:173], v136 offset:1024
	ds_read_b128 v[174:177], v136 offset:2048
	ds_read_b128 v[178:181], v136 offset:3072
	v_lshl_add_u64 v[136:137], s[48:49], 0, v[132:133]
	s_add_i32 m0, s94, 0xc000
	ds_read_b128 v[202:205], v165
	ds_read_b128 v[208:211], v165 offset:1024
	ds_read_b128 v[212:215], v165 offset:2048
	ds_read_b128 v[216:219], v165 offset:3072
	ds_read_b128 v[220:223], v165 offset:4096
	ds_read_b128 v[224:227], v165 offset:5120
	ds_read_b128 v[228:231], v165 offset:6144
	ds_read_b128 v[232:235], v165 offset:7168
	global_load_lds_dwordx4 v[136:137], off
	v_lshl_add_u64 v[136:137], s[48:49], 0, v[134:135]
	s_add_i32 m0, s94, 0xe000
	s_nop 0
	global_load_lds_dwordx4 v[136:137], off
	s_waitcnt vmcnt(8)
	s_waitcnt lgkmcnt(0)
	s_barrier
; #define PG8_STAGE(bufoff, gbase, voff) do { _Pragma("unroll") for (int _i = 0; _i < 2; ++_i) \
;         __builtin_amdgcn_global_load_lds((const unsigned*)((const char*)(gbase) + (voff)[_i]), (PG8_LAS unsigned*)(lds + (bufoff) + ldsw + _i * 8192), 16, 0, 0); } while (0)
; #define PG8_LDA(dst, b, h) do { _Pragma("unroll") for (int m = 0; m < 4; ++m) _Pragma("unroll") for (int k = 0; k < 2; ++k) dst[m][k] = *(const PG8_LAS bf16x8*)(lds + PG8_SA(b, h) + aoff + m * 2048 + k * 1024); } while (0)
; #define PG8_MMA(ai, bj, At, Bt) do { __builtin_amdgcn_s_setprio(1); _Pragma("unroll") for (int m = 0; m < 4; ++m) _Pragma("unroll") for (int n = 0; n < 2; ++n) _Pragma("unroll") for (int k = 0; k < 2; ++k) \
;         acc[ai][bj][m][n] = __builtin_amdgcn_mfma_f32_16x16x32_bf16(Bt[n][k], At[m][k], acc[ai][bj][m][n], 0, 0, 0); __builtin_amdgcn_s_setprio(0); } while (0)
; #define PG8_WAIT_V(n) asm volatile("s_waitcnt vmcnt(" #n ")" ::: "memory")
; #define PG8_WAIT_L(n) asm volatile("s_waitcnt lgkmcnt(" #n ")" ::: "memory")
; #define PG8_BAR __builtin_amdgcn_s_barrier()
; #define PG8_SCHED __builtin_amdgcn_sched_barrier(0)
; template <class Epi, class Sched, bool ALIGN_EPI = false, bool SP2 = false>
; __device__ __forceinline__ void gemm_phase(PG8_LAS unsigned char* lds, const Gemm g, const Sched& S, const Epi& E) {
;     ...
;             PG8_WAIT_V(8); PG8_WAIT_L(0); PG8_BAR; PG8_MMA(0, 0, At, B0); PG8_MMA(0, 1, At, B1); PG8_BAR; PG8_SCHED;
;             PG8_LDA(At, 0, 1); PG8_STAGE(PG8_SB(0, 0), b2, voffB); PG8_STAGE(PG8_SB(0, 1), b2 + hstep, voffB); PG8_STAGE(PG8_SA(0, 0), a2, voffA);
;             PG8_WAIT_V(8); PG8_WAIT_L(0); PG8_BAR; PG8_MMA(1, 0, At, B0); PG8_MMA(1, 1, At, B1); PG8_BAR; PG8_SCHED;
	s_setprio 1
	s_waitcnt lgkmcnt(0)
	v_mfma_f32_16x16x32_bf16 v[126:129], v[148:151], v[202:205], 0
	v_mfma_f32_16x16x32_bf16 v[122:125], v[156:159], v[202:205], 0
	v_mfma_f32_16x16x32_bf16 v[110:113], v[148:151], v[212:215], 0
	v_mfma_f32_16x16x32_bf16 v[106:109], v[156:159], v[212:215], 0
	v_mfma_f32_16x16x32_bf16 v[94:97], v[148:151], v[220:223], 0
	v_mfma_f32_16x16x32_bf16 v[90:93], v[156:159], v[220:223], 0
	v_mfma_f32_16x16x32_bf16 v[78:81], v[148:151], v[228:231], 0
	v_mfma_f32_16x16x32_bf16 v[74:77], v[156:159], v[228:231], 0
	v_mfma_f32_16x16x32_bf16 v[126:129], v[152:155], v[208:211], v[126:129]
	v_mfma_f32_16x16x32_bf16 v[122:125], v[160:163], v[208:211], v[122:125]
	v_mfma_f32_16x16x32_bf16 v[110:113], v[152:155], v[216:219], v[110:113]
	v_mfma_f32_16x16x32_bf16 v[106:109], v[160:163], v[216:219], v[106:109]
	v_mfma_f32_16x16x32_bf16 v[94:97], v[152:155], v[224:227], v[94:97]
	v_mfma_f32_16x16x32_bf16 v[90:93], v[160:163], v[224:227], v[90:93]
	v_mfma_f32_16x16x32_bf16 v[78:81], v[152:155], v[232:235], v[78:81]
	v_mfma_f32_16x16x32_bf16 v[74:77], v[160:163], v[232:235], v[74:77]
	s_setprio 0
	s_setprio 1
	v_mfma_f32_16x16x32_bf16 v[118:121], v[166:169], v[202:205], 0
	v_mfma_f32_16x16x32_bf16 v[114:117], v[174:177], v[202:205], 0
	v_mfma_f32_16x16x32_bf16 v[102:105], v[166:169], v[212:215], 0
	v_mfma_f32_16x16x32_bf16 v[98:101], v[174:177], v[212:215], 0
	v_mfma_f32_16x16x32_bf16 v[86:89], v[166:169], v[220:223], 0
	v_mfma_f32_16x16x32_bf16 v[82:85], v[174:177], v[220:223], 0
	v_mfma_f32_16x16x32_bf16 v[70:73], v[166:169], v[228:231], 0
	v_mfma_f32_16x16x32_bf16 v[66:69], v[174:177], v[228:231], 0
	v_mfma_f32_16x16x32_bf16 v[118:121], v[170:173], v[208:211], v[118:121]
	v_mfma_f32_16x16x32_bf16 v[114:117], v[178:181], v[208:211], v[114:117]
	v_mfma_f32_16x16x32_bf16 v[102:105], v[170:173], v[216:219], v[102:105]
	v_mfma_f32_16x16x32_bf16 v[98:101], v[178:181], v[216:219], v[98:101]
	v_mfma_f32_16x16x32_bf16 v[86:89], v[170:173], v[224:227], v[86:89]
	v_mfma_f32_16x16x32_bf16 v[82:85], v[178:181], v[224:227], v[82:85]
	v_mfma_f32_16x16x32_bf16 v[70:73], v[170:173], v[232:235], v[70:73]
	v_mfma_f32_16x16x32_bf16 v[66:69], v[178:181], v[232:235], v[66:69]
	s_setprio 0
	s_barrier
	s_add_i32 s59, s59, s93
	v_lshl_add_u64 v[136:137], vcc, 0, v[0:1]
	s_mov_b32 m0, s59
	ds_read_b128 v[202:205], v165 offset:16384
	ds_read_b128 v[208:211], v165 offset:17408
	ds_read_b128 v[212:215], v165 offset:18432
	ds_read_b128 v[216:219], v165 offset:19456
	ds_read_b128 v[220:223], v165 offset:20480
	ds_read_b128 v[224:227], v165 offset:21504
	ds_read_b128 v[228:231], v165 offset:22528
	ds_read_b128 v[232:235], v165 offset:23552
	global_load_lds_dwordx4 v[136:137], off
	s_add_i32 m0, s59, 0x2000
	v_lshl_add_u64 v[144:145], vcc, 0, v[130:131]
	s_add_u32 vcc_lo, vcc_lo, s10
	s_addc_u32 vcc_hi, vcc_hi, 0
	s_add_i32 s59, s83, s93
	global_load_lds_dwordx4 v[144:145], off
	v_lshl_add_u64 v[182:183], vcc, 0, v[0:1]
	s_mov_b32 m0, s59
	v_lshl_add_u64 v[236:237], vcc, 0, v[130:131]
	global_load_lds_dwordx4 v[182:183], off
	s_add_i32 m0, s59, 0x2000
	v_lshl_add_u64 v[238:239], s[76:77], 0, v[0:1]
	global_load_lds_dwordx4 v[236:237], off
	s_mov_b32 m0, s94
	v_lshl_add_u64 v[240:241], s[76:77], 0, v[130:131]
	global_load_lds_dwordx4 v[238:239], off
	s_mov_b32 m0, s95
	s_nop 0
	global_load_lds_dwordx4 v[240:241], off
	s_waitcnt vmcnt(8)
	s_waitcnt lgkmcnt(0)
	s_barrier
	s_setprio 1
	s_waitcnt lgkmcnt(0)
	v_mfma_f32_16x16x32_bf16 v[62:65], v[148:151], v[202:205], 0
	v_mfma_f32_16x16x32_bf16 v[58:61], v[156:159], v[202:205], 0
	v_mfma_f32_16x16x32_bf16 v[46:49], v[148:151], v[212:215], 0
	v_mfma_f32_16x16x32_bf16 v[42:45], v[156:159], v[212:215], 0
	v_mfma_f32_16x16x32_bf16 v[30:33], v[148:151], v[220:223], 0
	v_mfma_f32_16x16x32_bf16 v[26:29], v[156:159], v[220:223], 0
	v_mfma_f32_16x16x32_bf16 v[14:17], v[148:151], v[228:231], 0
	v_mfma_f32_16x16x32_bf16 v[10:13], v[156:159], v[228:231], 0
	v_mfma_f32_16x16x32_bf16 v[62:65], v[152:155], v[208:211], v[62:65]
	v_mfma_f32_16x16x32_bf16 v[58:61], v[160:163], v[208:211], v[58:61]
	v_mfma_f32_16x16x32_bf16 v[46:49], v[152:155], v[216:219], v[46:49]
	v_mfma_f32_16x16x32_bf16 v[42:45], v[160:163], v[216:219], v[42:45]
	v_mfma_f32_16x16x32_bf16 v[30:33], v[152:155], v[224:227], v[30:33]
	v_mfma_f32_16x16x32_bf16 v[26:29], v[160:163], v[224:227], v[26:29]
	v_mfma_f32_16x16x32_bf16 v[14:17], v[152:155], v[232:235], v[14:17]
	v_mfma_f32_16x16x32_bf16 v[10:13], v[160:163], v[232:235], v[10:13]
	s_setprio 0
	s_setprio 1
	v_mfma_f32_16x16x32_bf16 v[54:57], v[166:169], v[202:205], 0
	v_mfma_f32_16x16x32_bf16 v[50:53], v[174:177], v[202:205], 0
	v_mfma_f32_16x16x32_bf16 v[38:41], v[166:169], v[212:215], 0
	v_mfma_f32_16x16x32_bf16 v[34:37], v[174:177], v[212:215], 0
	v_mfma_f32_16x16x32_bf16 v[22:25], v[166:169], v[220:223], 0
	v_mfma_f32_16x16x32_bf16 v[18:21], v[174:177], v[220:223], 0
	v_mfma_f32_16x16x32_bf16 v[6:9], v[166:169], v[228:231], 0
	v_mfma_f32_16x16x32_bf16 v[2:5], v[174:177], v[228:231], 0
	v_mfma_f32_16x16x32_bf16 v[54:57], v[170:173], v[208:211], v[54:57]
	v_mfma_f32_16x16x32_bf16 v[50:53], v[178:181], v[208:211], v[50:53]
	v_mfma_f32_16x16x32_bf16 v[38:41], v[170:173], v[216:219], v[38:41]
	v_mfma_f32_16x16x32_bf16 v[34:37], v[178:181], v[216:219], v[34:37]
	v_mfma_f32_16x16x32_bf16 v[22:25], v[170:173], v[224:227], v[22:25]
	v_mfma_f32_16x16x32_bf16 v[18:21], v[178:181], v[224:227], v[18:21]
	v_mfma_f32_16x16x32_bf16 v[6:9], v[170:173], v[232:235], v[6:9]
	v_mfma_f32_16x16x32_bf16 v[2:5], v[178:181], v[232:235], v[2:5]
	s_setprio 0
	s_barrier
; #define PG8_STAGE(bufoff, gbase, voff) do { _Pragma("unroll") for (int _i = 0; _i < 2; ++_i) \
;         __builtin_amdgcn_global_load_lds((const unsigned*)((const char*)(gbase) + (voff)[_i]), (PG8_LAS unsigned*)(lds + (bufoff) + ldsw + _i * 8192), 16, 0, 0); } while (0)
; #define PG8_LDA(dst, b, h) do { _Pragma("unroll") for (int m = 0; m < 4; ++m) _Pragma("unroll") for (int k = 0; k < 2; ++k) dst[m][k] = *(const PG8_LAS bf16x8*)(lds + PG8_SA(b, h) + aoff + m * 2048 + k * 1024); } while (0)
; #define PG8_LDB(dst, b, h) do { _Pragma("unroll") for (int n = 0; n < 2; ++n) _Pragma("unroll") for (int k = 0; k < 2; ++k) dst[n][k] = *(const PG8_LAS bf16x8*)(lds + PG8_SB(b, h) + boff + n * 2048 + k * 1024); } while (0)
; #define PG8_MMA(ai, bj, At, Bt) do { __builtin_amdgcn_s_setprio(1); _Pragma("unroll") for (int m = 0; m < 4; ++m) _Pragma("unroll") for (int n = 0; n < 2; ++n) _Pragma("unroll") for (int k = 0; k < 2; ++k) \
;         acc[ai][bj][m][n] = __builtin_amdgcn_mfma_f32_16x16x32_bf16(Bt[n][k], At[m][k], acc[ai][bj][m][n], 0, 0, 0); __builtin_amdgcn_s_setprio(0); } while (0)
; #define PG8_WAIT_V(n) asm volatile("s_waitcnt vmcnt(" #n ")" ::: "memory")
; #define PG8_WAIT_L(n) asm volatile("s_waitcnt lgkmcnt(" #n ")" ::: "memory")
; #define PG8_BAR __builtin_amdgcn_s_barrier()
; #define PG8_SCHED __builtin_amdgcn_sched_barrier(0)
; template <class Epi, class Sched, bool ALIGN_EPI = false, bool SP2 = false>
; __device__ __forceinline__ void gemm_phase(PG8_LAS unsigned char* lds, const Gemm g, const Sched& S, const Epi& E) {
;     ...
;             PG8_WAIT_V(8); PG8_WAIT_L(0); PG8_BAR; PG8_MMA(1, 0, At, B0); PG8_MMA(1, 1, At, B1); PG8_BAR; PG8_SCHED;
;             PG8_LDB(B0, 1, 0); PG8_LDB(B1, 1, 1); PG8_SCHED; PG8_LDA(At, 1, 0); PG8_STAGE(PG8_SA(0, 1), a2 + hstep, voffA);
;             PG8_WAIT_V(8); PG8_WAIT_L(0); PG8_BAR; PG8_MMA(0, 0, At, B0); PG8_MMA(0, 1, At, B1); PG8_BAR; PG8_SCHED;
	s_add_i32 s59, 0, 0x18000
	s_add_i32 s83, 0, 0x1c000
	v_add_u32_e32 v160, s59, v147
	v_add_u32_e32 v178, s83, v147
	ds_read_b128 v[148:151], v160
	ds_read_b128 v[152:155], v160 offset:1024
	ds_read_b128 v[156:159], v160 offset:2048
	ds_read_b128 v[160:163], v160 offset:3072
	ds_read_b128 v[166:169], v178
	ds_read_b128 v[170:173], v178 offset:1024
	ds_read_b128 v[174:177], v178 offset:2048
	ds_read_b128 v[178:181], v178 offset:3072
	s_add_u32 s76, s76, s10
	s_addc_u32 s77, s77, 0
	s_mov_b32 m0, s84
	v_lshl_add_u64 v[242:243], s[76:77], 0, v[0:1]
	ds_read_b128 v[202:205], v165 offset:32768
	ds_read_b128 v[208:211], v165 offset:33792
	ds_read_b128 v[212:215], v165 offset:34816
	ds_read_b128 v[216:219], v165 offset:35840
	ds_read_b128 v[220:223], v165 offset:36864
	ds_read_b128 v[224:227], v165 offset:37888
	ds_read_b128 v[228:231], v165 offset:38912
	ds_read_b128 v[232:235], v165 offset:39936
	global_load_lds_dwordx4 v[242:243], off
	v_lshl_add_u64 v[242:243], s[76:77], 0, v[130:131]
	s_mov_b32 m0, s74
	s_nop 0
	global_load_lds_dwordx4 v[242:243], off
	s_waitcnt vmcnt(8)
	s_waitcnt lgkmcnt(0)
	s_barrier
	s_setprio 1
	s_waitcnt lgkmcnt(0)
	v_mfma_f32_16x16x32_bf16 v[126:129], v[148:151], v[202:205], v[126:129]
	v_mfma_f32_16x16x32_bf16 v[122:125], v[156:159], v[202:205], v[122:125]
	v_mfma_f32_16x16x32_bf16 v[110:113], v[148:151], v[212:215], v[110:113]
	v_mfma_f32_16x16x32_bf16 v[106:109], v[156:159], v[212:215], v[106:109]
	v_mfma_f32_16x16x32_bf16 v[94:97], v[148:151], v[220:223], v[94:97]
	v_mfma_f32_16x16x32_bf16 v[90:93], v[156:159], v[220:223], v[90:93]
	v_mfma_f32_16x16x32_bf16 v[78:81], v[148:151], v[228:231], v[78:81]
	v_mfma_f32_16x16x32_bf16 v[74:77], v[156:159], v[228:231], v[74:77]
	v_mfma_f32_16x16x32_bf16 v[126:129], v[152:155], v[208:211], v[126:129]
	v_mfma_f32_16x16x32_bf16 v[122:125], v[160:163], v[208:211], v[122:125]
	v_mfma_f32_16x16x32_bf16 v[110:113], v[152:155], v[216:219], v[110:113]
	v_mfma_f32_16x16x32_bf16 v[106:109], v[160:163], v[216:219], v[106:109]
	v_mfma_f32_16x16x32_bf16 v[94:97], v[152:155], v[224:227], v[94:97]
	v_mfma_f32_16x16x32_bf16 v[90:93], v[160:163], v[224:227], v[90:93]
	v_mfma_f32_16x16x32_bf16 v[78:81], v[152:155], v[232:235], v[78:81]
	v_mfma_f32_16x16x32_bf16 v[74:77], v[160:163], v[232:235], v[74:77]
	s_setprio 0
	s_setprio 1
	v_mfma_f32_16x16x32_bf16 v[118:121], v[166:169], v[202:205], v[118:121]
	v_mfma_f32_16x16x32_bf16 v[114:117], v[174:177], v[202:205], v[114:117]
	v_mfma_f32_16x16x32_bf16 v[102:105], v[166:169], v[212:215], v[102:105]
	v_mfma_f32_16x16x32_bf16 v[98:101], v[174:177], v[212:215], v[98:101]
	v_mfma_f32_16x16x32_bf16 v[86:89], v[166:169], v[220:223], v[86:89]
	v_mfma_f32_16x16x32_bf16 v[82:85], v[174:177], v[220:223], v[82:85]
	v_mfma_f32_16x16x32_bf16 v[70:73], v[166:169], v[228:231], v[70:73]
	v_mfma_f32_16x16x32_bf16 v[66:69], v[174:177], v[228:231], v[66:69]
	v_mfma_f32_16x16x32_bf16 v[118:121], v[170:173], v[208:211], v[118:121]
	v_mfma_f32_16x16x32_bf16 v[114:117], v[178:181], v[208:211], v[114:117]
	v_mfma_f32_16x16x32_bf16 v[102:105], v[170:173], v[216:219], v[102:105]
	v_mfma_f32_16x16x32_bf16 v[98:101], v[178:181], v[216:219], v[98:101]
	v_mfma_f32_16x16x32_bf16 v[86:89], v[170:173], v[224:227], v[86:89]
	v_mfma_f32_16x16x32_bf16 v[82:85], v[178:181], v[224:227], v[82:85]
	v_mfma_f32_16x16x32_bf16 v[70:73], v[170:173], v[232:235], v[70:73]
	v_mfma_f32_16x16x32_bf16 v[66:69], v[178:181], v[232:235], v[66:69]
	s_setprio 0
	s_barrier
; #define PG8_STAGE(bufoff, gbase, voff) do { _Pragma("unroll") for (int _i = 0; _i < 2; ++_i) \
;         __builtin_amdgcn_global_load_lds((const unsigned*)((const char*)(gbase) + (voff)[_i]), (PG8_LAS unsigned*)(lds + (bufoff) + ldsw + _i * 8192), 16, 0, 0); } while (0)
; #define PG8_LDA(dst, b, h) do { _Pragma("unroll") for (int m = 0; m < 4; ++m) _Pragma("unroll") for (int k = 0; k < 2; ++k) dst[m][k] = *(const PG8_LAS bf16x8*)(lds + PG8_SA(b, h) + aoff + m * 2048 + k * 1024); } while (0)
; #define PG8_LDB(dst, b, h) do { _Pragma("unroll") for (int n = 0; n < 2; ++n) _Pragma("unroll") for (int k = 0; k < 2; ++k) dst[n][k] = *(const PG8_LAS bf16x8*)(lds + PG8_SB(b, h) + boff + n * 2048 + k * 1024); } while (0)
; template <class Epi, class Sched, bool ALIGN_EPI = false, bool SP2 = false>
; __device__ __forceinline__ void gemm_phase(PG8_LAS unsigned char* lds, const Gemm g, const Sched& S, const Epi& E) {
;     ...
;         for (int t = 0; t < nt; t += 2) {
;             const bool last = (t == nt - 2);
;             const char* a1 = cA + (size_t)(t + 1) * kstep;
;             const char* a2 = last ? nA : cA + (size_t)(t + 2) * kstep; const char* b2 = last ? nB : cB + (size_t)(t + 2) * kstep;
;             const char* a3 = a2 + kstep; const char* b3 = b2 + kstep;
;             if (last && has_next) S.a_ready(nxt);
;             if constexpr (SP2) {
;             PG8_LDB(B0, 0, 0); PG8_LDB(B1, 0, 1); PG8_SCHED; PG8_LDA(At, 0, 0); PG8_STAGE(PG8_SA(1, 1), a1 + hstep, voffA);
;             PG8_WAIT_V(8); PG8_WAIT_L(0); PG8_BAR; PG8_MMA(0, 0, At, B0); PG8_MMA(0, 1, At, B1); PG8_BAR; PG8_SCHED;
;             PG8_LDA(At, 0, 1); PG8_STAGE(PG8_SB(0, 0), b2, voffB); PG8_STAGE(PG8_SB(0, 1), b2 + hstep, voffB); PG8_STAGE(PG8_SA(0, 0), a2, voffA);
;             PG8_WAIT_V(8); PG8_WAIT_L(0); PG8_BAR; PG8_MMA(1, 0, At, B0); PG8_MMA(1, 1, At, B1); PG8_BAR; PG8_SCHED;
;             PG8_LDB(B0, 1, 0); PG8_LDB(B1, 1, 1); PG8_SCHED; PG8_LDA(At, 1, 0); PG8_STAGE(PG8_SA(0, 1), a2 + hstep, voffA);
;             PG8_WAIT_V(8); PG8_WAIT_L(0); PG8_BAR; PG8_MMA(0, 0, At, B0); PG8_MMA(0, 1, At, B1); PG8_BAR; PG8_SCHED;
;             PG8_LDA(At, 1, 1); PG8_STAGE(PG8_SB(1, 0), b3, voffB); PG8_STAGE(PG8_SB(1, 1), b3 + hstep, voffB); PG8_STAGE(PG8_SA(1, 0), a3, voffA);
;             PG8_WAIT_V(8); PG8_WAIT_L(0); PG8_BAR; PG8_MMA(1, 0, At, B0); PG8_MMA(1, 1, At, B1); PG8_BAR; PG8_SCHED;
	s_add_i32 s59, s59, s93
	v_lshl_add_u64 v[136:137], v[136:137], 0, s[66:67]
	s_mov_b32 m0, s59
	ds_read_b128 v[202:205], v165 offset:49152
	ds_read_b128 v[208:211], v165 offset:50176
	ds_read_b128 v[212:215], v165 offset:51200
	ds_read_b128 v[216:219], v165 offset:52224
	ds_read_b128 v[220:223], v165 offset:53248
	ds_read_b128 v[224:227], v165 offset:54272
	ds_read_b128 v[228:231], v165 offset:55296
	ds_read_b128 v[232:235], v165 offset:56320
	global_load_lds_dwordx4 v[136:137], off
	v_lshl_add_u64 v[136:137], v[144:145], 0, s[66:67]
	s_add_i32 m0, s59, 0x2000
	s_add_i32 s59, s83, s93
	global_load_lds_dwordx4 v[136:137], off
	v_lshl_add_u64 v[136:137], v[182:183], 0, s[66:67]
	s_mov_b32 m0, s59
	s_nop 0
	global_load_lds_dwordx4 v[136:137], off
	v_lshl_add_u64 v[136:137], v[236:237], 0, s[66:67]
	s_add_i32 m0, s59, 0x2000
	s_nop 0
	global_load_lds_dwordx4 v[136:137], off
	v_lshl_add_u64 v[136:137], v[238:239], 0, s[66:67]
	s_mov_b32 m0, s73
	s_nop 0
	global_load_lds_dwordx4 v[136:137], off
	v_lshl_add_u64 v[136:137], v[240:241], 0, s[66:67]
	s_mov_b32 m0, s50
	s_nop 0
	global_load_lds_dwordx4 v[136:137], off
	s_waitcnt vmcnt(8)
	s_waitcnt lgkmcnt(0)
	s_barrier
	s_setprio 1
	s_waitcnt lgkmcnt(0)
	v_mfma_f32_16x16x32_bf16 v[62:65], v[148:151], v[202:205], v[62:65]
	v_mfma_f32_16x16x32_bf16 v[58:61], v[156:159], v[202:205], v[58:61]
	v_mfma_f32_16x16x32_bf16 v[46:49], v[148:151], v[212:215], v[46:49]
	v_mfma_f32_16x16x32_bf16 v[42:45], v[156:159], v[212:215], v[42:45]
	v_mfma_f32_16x16x32_bf16 v[30:33], v[148:151], v[220:223], v[30:33]
	v_mfma_f32_16x16x32_bf16 v[26:29], v[156:159], v[220:223], v[26:29]
	v_mfma_f32_16x16x32_bf16 v[14:17], v[148:151], v[228:231], v[14:17]
	v_mfma_f32_16x16x32_bf16 v[10:13], v[156:159], v[228:231], v[10:13]
	v_mfma_f32_16x16x32_bf16 v[62:65], v[152:155], v[208:211], v[62:65]
	v_mfma_f32_16x16x32_bf16 v[58:61], v[160:163], v[208:211], v[58:61]
	v_mfma_f32_16x16x32_bf16 v[46:49], v[152:155], v[216:219], v[46:49]
	v_mfma_f32_16x16x32_bf16 v[42:45], v[160:163], v[216:219], v[42:45]
	v_mfma_f32_16x16x32_bf16 v[30:33], v[152:155], v[224:227], v[30:33]
	v_mfma_f32_16x16x32_bf16 v[26:29], v[160:163], v[224:227], v[26:29]
	v_mfma_f32_16x16x32_bf16 v[14:17], v[152:155], v[232:235], v[14:17]
	v_mfma_f32_16x16x32_bf16 v[10:13], v[160:163], v[232:235], v[10:13]
	s_setprio 0
	s_setprio 1
	v_mfma_f32_16x16x32_bf16 v[54:57], v[166:169], v[202:205], v[54:57]
	v_mfma_f32_16x16x32_bf16 v[50:53], v[174:177], v[202:205], v[50:53]
	v_mfma_f32_16x16x32_bf16 v[38:41], v[166:169], v[212:215], v[38:41]
	v_mfma_f32_16x16x32_bf16 v[34:37], v[174:177], v[212:215], v[34:37]
	v_mfma_f32_16x16x32_bf16 v[22:25], v[166:169], v[220:223], v[22:25]
	v_mfma_f32_16x16x32_bf16 v[18:21], v[174:177], v[220:223], v[18:21]
	v_mfma_f32_16x16x32_bf16 v[6:9], v[166:169], v[228:231], v[6:9]
	v_mfma_f32_16x16x32_bf16 v[2:5], v[174:177], v[228:231], v[2:5]
	v_mfma_f32_16x16x32_bf16 v[54:57], v[170:173], v[208:211], v[54:57]
	v_mfma_f32_16x16x32_bf16 v[50:53], v[178:181], v[208:211], v[50:53]
	v_mfma_f32_16x16x32_bf16 v[38:41], v[170:173], v[216:219], v[38:41]
	v_mfma_f32_16x16x32_bf16 v[34:37], v[178:181], v[216:219], v[34:37]
	v_mfma_f32_16x16x32_bf16 v[22:25], v[170:173], v[224:227], v[22:25]
	v_mfma_f32_16x16x32_bf16 v[18:21], v[178:181], v[224:227], v[18:21]
	v_mfma_f32_16x16x32_bf16 v[6:9], v[170:173], v[232:235], v[6:9]
	v_mfma_f32_16x16x32_bf16 v[2:5], v[178:181], v[232:235], v[2:5]
	s_setprio 0
	s_barrier
	s_add_u32 s48, s48, 0x100
	s_addc_u32 s49, s49, 0
	s_add_u32 s80, s80, 0x100
	s_addc_u32 s81, s81, 0
	s_cmp_ge_u32 s82, s79
	s_mov_b32 s76, s82
	s_cbranch_scc0 .LBB0_849
	s_branch .Lkq_exit
	s_nop 0
	s_nop 0
	s_nop 0
	s_nop 0
	s_nop 0
	s_nop 0
	s_nop 0
	s_nop 0
